# GEMM K-loops: MFMAs of each 8-run reordered so consecutive MFMAs share one operand (bit-identical)
# baseline (speedup 1.0000x reference)
; #define PG8_STAGE(bufoff, gbase, voff) do { _Pragma("unroll") for (int _i = 0; _i < 2; ++_i) \
;         __builtin_amdgcn_global_load_lds((const unsigned*)((const char*)(gbase) + (voff)[_i]), (PG8_LAS unsigned*)(lds + (bufoff) + ldsw + _i * 8192), 16, 0, 0); } while (0)
; #define PG8_LDA(dst, b, h) do { _Pragma("unroll") for (int m = 0; m < 4; ++m) _Pragma("unroll") for (int k = 0; k < 2; ++k) dst[m][k] = *(const PG8_LAS bf16x8*)(lds + PG8_SA(b, h) + aoff + m * 2048 + k * 1024); } while (0)
; #define PG8_LDB(dst, b, h) do { _Pragma("unroll") for (int n = 0; n < 2; ++n) _Pragma("unroll") for (int k = 0; k < 2; ++k) dst[n][k] = *(const PG8_LAS bf16x8*)(lds + PG8_SB(b, h) + boff + n * 2048 + k * 1024); } while (0)
; #define PG8_MMA(ai, bj, At, Bt) do { __builtin_amdgcn_s_setprio(1); _Pragma("unroll") for (int m = 0; m < 4; ++m) _Pragma("unroll") for (int n = 0; n < 2; ++n) _Pragma("unroll") for (int k = 0; k < 2; ++k) \
;         acc[ai][bj][m][n] = __builtin_amdgcn_mfma_f32_16x16x32_bf16(Bt[n][k], At[m][k], acc[ai][bj][m][n], 0, 0, 0); __builtin_amdgcn_s_setprio(0); } while (0)
; #define PG8_WAIT_V(n) asm volatile("s_waitcnt vmcnt(" #n ")" ::: "memory")
; #define PG8_WAIT_L(n) asm volatile("s_waitcnt lgkmcnt(" #n ")" ::: "memory")
; #define PG8_BAR __builtin_amdgcn_s_barrier()
; #define PG8_SCHED __builtin_amdgcn_sched_barrier(0)
; template <class Epi, class Sched, bool ALIGN_EPI = false, bool SP2 = false>
; __device__ __forceinline__ void gemm_phase(PG8_LAS unsigned char* lds, const Gemm g, const Sched& S, const Epi& E, const int wave_) {
;     ...
;             PG8_LDB(B0, 0, 0); PG8_LDB(B1, 0, 1); PG8_SCHED; PG8_LDA(At, 0, 0); PG8_STAGE(PG8_SA(1, 1), a1 + hstep, voffA);
;             PG8_WAIT_V(8); PG8_WAIT_L(0); PG8_BAR; PG8_MMA(0, 0, At, B0); PG8_MMA(0, 1, At, B1); PG8_BAR; PG8_SCHED;
;             PG8_LDA(At, 0, 1); PG8_STAGE(PG8_SB(0, 0), b2, voffB); PG8_STAGE(PG8_SB(0, 1), b2 + hstep, voffB); PG8_STAGE(PG8_SA(0, 0), a2, voffA);
.LBB0_129:
	s_waitcnt lgkmcnt(0)
	ds_read_b128 v[158:161], v202
	ds_read_b128 v[162:165], v202 offset:1024
	ds_read_b128 v[166:169], v202 offset:2048
	ds_read_b128 v[170:173], v202 offset:3072
	ds_read_b128 v[174:177], v205
	ds_read_b128 v[178:181], v205 offset:1024
	ds_read_b128 v[182:185], v205 offset:2048
	ds_read_b128 v[186:189], v205 offset:3072
	s_add_u32 s23, s46, 0xfff80080
	s_addc_u32 s24, s47, -1
	s_cmp_eq_u32 s22, 28
	s_cselect_b32 s51, s19, s24
	s_cselect_b32 s50, s39, s23
	s_cselect_b32 s49, s37, s97
	s_cselect_b32 s48, vcc_lo, vcc_hi
	v_lshl_add_u64 v[238:239], s[46:47], 0, v[148:149]
	s_add_i32 m0, s53, 0xc000
	ds_read_b128 v[206:209], v203
	ds_read_b128 v[210:213], v203 offset:1024
	ds_read_b128 v[214:217], v203 offset:2048
	ds_read_b128 v[218:221], v203 offset:3072
	ds_read_b128 v[222:225], v203 offset:4096
	ds_read_b128 v[226:229], v203 offset:5120
	ds_read_b128 v[230:233], v203 offset:6144
	ds_read_b128 v[234:237], v203 offset:7168
	global_load_lds_dwordx4 v[238:239], off
	v_lshl_add_u64 v[238:239], s[46:47], 0, v[150:151]
	s_add_i32 m0, s53, 0xe000
	s_nop 0
	global_load_lds_dwordx4 v[238:239], off
	s_waitcnt vmcnt(8)
	s_waitcnt lgkmcnt(0)
	s_barrier
	s_setprio 1
	s_waitcnt lgkmcnt(0)
	v_mfma_f32_16x16x32_bf16 v[124:127], v[158:161], v[206:209], v[124:127]
	v_mfma_f32_16x16x32_bf16 v[116:119], v[166:169], v[206:209], v[116:119]
	v_mfma_f32_16x16x32_bf16 v[100:103], v[166:169], v[214:217], v[100:103]
	v_mfma_f32_16x16x32_bf16 v[108:111], v[158:161], v[214:217], v[108:111]
	v_mfma_f32_16x16x32_bf16 v[92:95], v[158:161], v[222:225], v[92:95]
	v_mfma_f32_16x16x32_bf16 v[84:87], v[166:169], v[222:225], v[84:87]
	v_mfma_f32_16x16x32_bf16 v[68:71], v[166:169], v[230:233], v[68:71]
	v_mfma_f32_16x16x32_bf16 v[76:79], v[158:161], v[230:233], v[76:79]
	v_mfma_f32_16x16x32_bf16 v[124:127], v[162:165], v[210:213], v[124:127]
	v_mfma_f32_16x16x32_bf16 v[116:119], v[170:173], v[210:213], v[116:119]
	v_mfma_f32_16x16x32_bf16 v[100:103], v[170:173], v[218:221], v[100:103]
	v_mfma_f32_16x16x32_bf16 v[108:111], v[162:165], v[218:221], v[108:111]
	v_mfma_f32_16x16x32_bf16 v[92:95], v[162:165], v[226:229], v[92:95]
	v_mfma_f32_16x16x32_bf16 v[84:87], v[170:173], v[226:229], v[84:87]
	v_mfma_f32_16x16x32_bf16 v[68:71], v[170:173], v[234:237], v[68:71]
	v_mfma_f32_16x16x32_bf16 v[76:79], v[162:165], v[234:237], v[76:79]
	s_setprio 0
	s_setprio 1
	v_mfma_f32_16x16x32_bf16 v[120:123], v[174:177], v[206:209], v[120:123]
	v_mfma_f32_16x16x32_bf16 v[112:115], v[182:185], v[206:209], v[112:115]
	v_mfma_f32_16x16x32_bf16 v[96:99], v[182:185], v[214:217], v[96:99]
	v_mfma_f32_16x16x32_bf16 v[104:107], v[174:177], v[214:217], v[104:107]
	v_mfma_f32_16x16x32_bf16 v[88:91], v[174:177], v[222:225], v[88:91]
	v_mfma_f32_16x16x32_bf16 v[80:83], v[182:185], v[222:225], v[80:83]
	v_mfma_f32_16x16x32_bf16 v[64:67], v[182:185], v[230:233], v[64:67]
	v_mfma_f32_16x16x32_bf16 v[72:75], v[174:177], v[230:233], v[72:75]
	v_mfma_f32_16x16x32_bf16 v[120:123], v[178:181], v[210:213], v[120:123]
	v_mfma_f32_16x16x32_bf16 v[112:115], v[186:189], v[210:213], v[112:115]
	v_mfma_f32_16x16x32_bf16 v[96:99], v[186:189], v[218:221], v[96:99]
	v_mfma_f32_16x16x32_bf16 v[104:107], v[178:181], v[218:221], v[104:107]
	v_mfma_f32_16x16x32_bf16 v[88:91], v[178:181], v[226:229], v[88:91]
	v_mfma_f32_16x16x32_bf16 v[80:83], v[186:189], v[226:229], v[80:83]
	v_mfma_f32_16x16x32_bf16 v[64:67], v[186:189], v[234:237], v[64:67]
	v_mfma_f32_16x16x32_bf16 v[72:75], v[178:181], v[234:237], v[72:75]
	s_setprio 0
	s_barrier
	s_add_i32 s23, s67, s52
	v_lshl_add_u64 v[238:239], s[48:49], 0, v[130:131]
	s_mov_b32 m0, s23
	ds_read_b128 v[206:209], v203 offset:16384
	ds_read_b128 v[210:213], v203 offset:17408
	ds_read_b128 v[214:217], v203 offset:18432
	ds_read_b128 v[218:221], v203 offset:19456
	ds_read_b128 v[222:225], v203 offset:20480
	ds_read_b128 v[226:229], v203 offset:21504
	ds_read_b128 v[230:233], v203 offset:22528
	ds_read_b128 v[234:237], v203 offset:23552
	global_load_lds_dwordx4 v[238:239], off
	s_add_i32 m0, s23, 0x2000
	s_add_u32 s24, s48, 0x80000
	v_lshl_add_u64 v[240:241], s[48:49], 0, v[134:135]
	s_addc_u32 s25, s49, 0
	s_add_i32 s23, s71, s52
	global_load_lds_dwordx4 v[240:241], off
	v_lshl_add_u64 v[242:243], s[24:25], 0, v[130:131]
	s_mov_b32 m0, s23
	v_lshl_add_u64 v[244:245], s[50:51], 0, v[132:133]
	global_load_lds_dwordx4 v[242:243], off
	v_lshl_add_u64 v[242:243], s[24:25], 0, v[134:135]
	s_add_i32 m0, s23, 0x2000
	s_nop 0
	global_load_lds_dwordx4 v[242:243], off
	v_lshl_add_u64 v[242:243], s[50:51], 0, v[128:129]
	s_mov_b32 m0, s53
	s_nop 0
	global_load_lds_dwordx4 v[242:243], off
	s_mov_b32 m0, s54
	s_nop 0
	global_load_lds_dwordx4 v[244:245], off
	s_waitcnt vmcnt(8)
	s_waitcnt lgkmcnt(0)
	s_barrier
; #define PG8_STAGE(bufoff, gbase, voff) do { _Pragma("unroll") for (int _i = 0; _i < 2; ++_i) \
;         __builtin_amdgcn_global_load_lds((const unsigned*)((const char*)(gbase) + (voff)[_i]), (PG8_LAS unsigned*)(lds + (bufoff) + ldsw + _i * 8192), 16, 0, 0); } while (0)
; #define PG8_LDA(dst, b, h) do { _Pragma("unroll") for (int m = 0; m < 4; ++m) _Pragma("unroll") for (int k = 0; k < 2; ++k) dst[m][k] = *(const PG8_LAS bf16x8*)(lds + PG8_SA(b, h) + aoff + m * 2048 + k * 1024); } while (0)
; #define PG8_LDB(dst, b, h) do { _Pragma("unroll") for (int n = 0; n < 2; ++n) _Pragma("unroll") for (int k = 0; k < 2; ++k) dst[n][k] = *(const PG8_LAS bf16x8*)(lds + PG8_SB(b, h) + boff + n * 2048 + k * 1024); } while (0)
; #define PG8_MMA(ai, bj, At, Bt) do { __builtin_amdgcn_s_setprio(1); _Pragma("unroll") for (int m = 0; m < 4; ++m) _Pragma("unroll") for (int n = 0; n < 2; ++n) _Pragma("unroll") for (int k = 0; k < 2; ++k) \
;         acc[ai][bj][m][n] = __builtin_amdgcn_mfma_f32_16x16x32_bf16(Bt[n][k], At[m][k], acc[ai][bj][m][n], 0, 0, 0); __builtin_amdgcn_s_setprio(0); } while (0)
; #define PG8_WAIT_V(n) asm volatile("s_waitcnt vmcnt(" #n ")" ::: "memory")
; #define PG8_WAIT_L(n) asm volatile("s_waitcnt lgkmcnt(" #n ")" ::: "memory")
; #define PG8_BAR __builtin_amdgcn_s_barrier()
; #define PG8_SCHED __builtin_amdgcn_sched_barrier(0)
; template <class Epi, class Sched, bool ALIGN_EPI = false, bool SP2 = false>
; __device__ __forceinline__ void gemm_phase(PG8_LAS unsigned char* lds, const Gemm g, const Sched& S, const Epi& E, const int wave_) {
;     ...
;             PG8_WAIT_V(8); PG8_WAIT_L(0); PG8_BAR; PG8_MMA(1, 0, At, B0); PG8_MMA(1, 1, At, B1); PG8_BAR; PG8_SCHED;
;             PG8_LDB(B0, 1, 0); PG8_LDB(B1, 1, 1); PG8_SCHED; PG8_LDA(At, 1, 0); PG8_STAGE(PG8_SA(0, 1), a2 + hstep, voffA);
;             PG8_WAIT_V(8); PG8_WAIT_L(0); PG8_BAR; PG8_MMA(0, 0, At, B0); PG8_MMA(0, 1, At, B1); PG8_BAR; PG8_SCHED;
	s_setprio 1
	s_waitcnt lgkmcnt(0)
	v_mfma_f32_16x16x32_bf16 v[60:63], v[158:161], v[206:209], v[60:63]
	v_mfma_f32_16x16x32_bf16 v[52:55], v[166:169], v[206:209], v[52:55]
	v_mfma_f32_16x16x32_bf16 v[36:39], v[166:169], v[214:217], v[36:39]
	v_mfma_f32_16x16x32_bf16 v[44:47], v[158:161], v[214:217], v[44:47]
	v_mfma_f32_16x16x32_bf16 v[28:31], v[158:161], v[222:225], v[28:31]
	v_mfma_f32_16x16x32_bf16 v[20:23], v[166:169], v[222:225], v[20:23]
	v_mfma_f32_16x16x32_bf16 v[4:7], v[166:169], v[230:233], v[4:7]
	v_mfma_f32_16x16x32_bf16 v[12:15], v[158:161], v[230:233], v[12:15]
	v_mfma_f32_16x16x32_bf16 v[60:63], v[162:165], v[210:213], v[60:63]
	v_mfma_f32_16x16x32_bf16 v[52:55], v[170:173], v[210:213], v[52:55]
	v_mfma_f32_16x16x32_bf16 v[36:39], v[170:173], v[218:221], v[36:39]
	v_mfma_f32_16x16x32_bf16 v[44:47], v[162:165], v[218:221], v[44:47]
	v_mfma_f32_16x16x32_bf16 v[28:31], v[162:165], v[226:229], v[28:31]
	v_mfma_f32_16x16x32_bf16 v[20:23], v[170:173], v[226:229], v[20:23]
	v_mfma_f32_16x16x32_bf16 v[4:7], v[170:173], v[234:237], v[4:7]
	v_mfma_f32_16x16x32_bf16 v[12:15], v[162:165], v[234:237], v[12:15]
	s_setprio 0
	s_setprio 1
	v_mfma_f32_16x16x32_bf16 v[56:59], v[174:177], v[206:209], v[56:59]
	v_mfma_f32_16x16x32_bf16 v[48:51], v[182:185], v[206:209], v[48:51]
	v_mfma_f32_16x16x32_bf16 v[32:35], v[182:185], v[214:217], v[32:35]
	v_mfma_f32_16x16x32_bf16 v[40:43], v[174:177], v[214:217], v[40:43]
	v_mfma_f32_16x16x32_bf16 v[24:27], v[174:177], v[222:225], v[24:27]
	v_mfma_f32_16x16x32_bf16 v[16:19], v[182:185], v[222:225], v[16:19]
	v_mfma_f32_16x16x32_bf16 v[0:3], v[182:185], v[230:233], v[0:3]
	v_mfma_f32_16x16x32_bf16 v[8:11], v[174:177], v[230:233], v[8:11]
	v_mfma_f32_16x16x32_bf16 v[56:59], v[178:181], v[210:213], v[56:59]
	v_mfma_f32_16x16x32_bf16 v[48:51], v[186:189], v[210:213], v[48:51]
	v_mfma_f32_16x16x32_bf16 v[32:35], v[186:189], v[218:221], v[32:35]
	v_mfma_f32_16x16x32_bf16 v[40:43], v[178:181], v[218:221], v[40:43]
	v_mfma_f32_16x16x32_bf16 v[24:27], v[178:181], v[226:229], v[24:27]
	v_mfma_f32_16x16x32_bf16 v[16:19], v[186:189], v[226:229], v[16:19]
	v_mfma_f32_16x16x32_bf16 v[0:3], v[186:189], v[234:237], v[0:3]
	v_mfma_f32_16x16x32_bf16 v[8:11], v[178:181], v[234:237], v[8:11]
	s_setprio 0
	s_barrier
	s_add_i32 s23, 0, 0x18000
	s_add_i32 s86, 0, 0x1c000
	v_add_u32_e32 v170, s23, v191
	v_add_u32_e32 v186, s86, v191
	ds_read_b128 v[158:161], v170
	ds_read_b128 v[162:165], v170 offset:1024
	ds_read_b128 v[166:169], v170 offset:2048
	ds_read_b128 v[170:173], v170 offset:3072
	ds_read_b128 v[174:177], v186
	ds_read_b128 v[178:181], v186 offset:1024
	ds_read_b128 v[182:185], v186 offset:2048
	ds_read_b128 v[186:189], v186 offset:3072
	s_add_u32 s24, s50, 0x80000
	s_addc_u32 s25, s51, 0
	s_mov_b32 m0, s55
	v_lshl_add_u64 v[246:247], s[24:25], 0, v[128:129]
	ds_read_b128 v[206:209], v203 offset:32768
	ds_read_b128 v[210:213], v203 offset:33792
	ds_read_b128 v[214:217], v203 offset:34816
	ds_read_b128 v[218:221], v203 offset:35840
	ds_read_b128 v[222:225], v203 offset:36864
	ds_read_b128 v[226:229], v203 offset:37888
	ds_read_b128 v[230:233], v203 offset:38912
	ds_read_b128 v[234:237], v203 offset:39936
	global_load_lds_dwordx4 v[246:247], off
	v_lshl_add_u64 v[246:247], s[24:25], 0, v[132:133]
	s_mov_b32 m0, s56
	s_nop 0
	global_load_lds_dwordx4 v[246:247], off
	s_waitcnt vmcnt(8)
	s_waitcnt lgkmcnt(0)
	s_barrier
	s_setprio 1
	s_waitcnt lgkmcnt(0)
	v_mfma_f32_16x16x32_bf16 v[124:127], v[158:161], v[206:209], v[124:127]
	v_mfma_f32_16x16x32_bf16 v[116:119], v[166:169], v[206:209], v[116:119]
	v_mfma_f32_16x16x32_bf16 v[100:103], v[166:169], v[214:217], v[100:103]
	v_mfma_f32_16x16x32_bf16 v[108:111], v[158:161], v[214:217], v[108:111]
	v_mfma_f32_16x16x32_bf16 v[92:95], v[158:161], v[222:225], v[92:95]
	v_mfma_f32_16x16x32_bf16 v[84:87], v[166:169], v[222:225], v[84:87]
	v_mfma_f32_16x16x32_bf16 v[68:71], v[166:169], v[230:233], v[68:71]
	v_mfma_f32_16x16x32_bf16 v[76:79], v[158:161], v[230:233], v[76:79]
	v_mfma_f32_16x16x32_bf16 v[124:127], v[162:165], v[210:213], v[124:127]
	v_mfma_f32_16x16x32_bf16 v[116:119], v[170:173], v[210:213], v[116:119]
	v_mfma_f32_16x16x32_bf16 v[100:103], v[170:173], v[218:221], v[100:103]
	v_mfma_f32_16x16x32_bf16 v[108:111], v[162:165], v[218:221], v[108:111]
	v_mfma_f32_16x16x32_bf16 v[92:95], v[162:165], v[226:229], v[92:95]
	v_mfma_f32_16x16x32_bf16 v[84:87], v[170:173], v[226:229], v[84:87]
	v_mfma_f32_16x16x32_bf16 v[68:71], v[170:173], v[234:237], v[68:71]
	v_mfma_f32_16x16x32_bf16 v[76:79], v[162:165], v[234:237], v[76:79]
	s_setprio 0
	s_setprio 1
	v_mfma_f32_16x16x32_bf16 v[120:123], v[174:177], v[206:209], v[120:123]
	v_mfma_f32_16x16x32_bf16 v[112:115], v[182:185], v[206:209], v[112:115]
	v_mfma_f32_16x16x32_bf16 v[96:99], v[182:185], v[214:217], v[96:99]
	v_mfma_f32_16x16x32_bf16 v[104:107], v[174:177], v[214:217], v[104:107]
	v_mfma_f32_16x16x32_bf16 v[88:91], v[174:177], v[222:225], v[88:91]
	v_mfma_f32_16x16x32_bf16 v[80:83], v[182:185], v[222:225], v[80:83]
	v_mfma_f32_16x16x32_bf16 v[64:67], v[182:185], v[230:233], v[64:67]
	v_mfma_f32_16x16x32_bf16 v[72:75], v[174:177], v[230:233], v[72:75]
	v_mfma_f32_16x16x32_bf16 v[120:123], v[178:181], v[210:213], v[120:123]
	v_mfma_f32_16x16x32_bf16 v[112:115], v[186:189], v[210:213], v[112:115]
	v_mfma_f32_16x16x32_bf16 v[96:99], v[186:189], v[218:221], v[96:99]
	v_mfma_f32_16x16x32_bf16 v[104:107], v[178:181], v[218:221], v[104:107]
	v_mfma_f32_16x16x32_bf16 v[88:91], v[178:181], v[226:229], v[88:91]
	v_mfma_f32_16x16x32_bf16 v[80:83], v[186:189], v[226:229], v[80:83]
	v_mfma_f32_16x16x32_bf16 v[64:67], v[186:189], v[234:237], v[64:67]
	v_mfma_f32_16x16x32_bf16 v[72:75], v[178:181], v[234:237], v[72:75]
	s_setprio 0
	s_barrier
; #define PG8_STAGE(bufoff, gbase, voff) do { _Pragma("unroll") for (int _i = 0; _i < 2; ++_i) \
;         __builtin_amdgcn_global_load_lds((const unsigned*)((const char*)(gbase) + (voff)[_i]), (PG8_LAS unsigned*)(lds + (bufoff) + ldsw + _i * 8192), 16, 0, 0); } while (0)
; #define PG8_LDA(dst, b, h) do { _Pragma("unroll") for (int m = 0; m < 4; ++m) _Pragma("unroll") for (int k = 0; k < 2; ++k) dst[m][k] = *(const PG8_LAS bf16x8*)(lds + PG8_SA(b, h) + aoff + m * 2048 + k * 1024); } while (0)
; #define PG8_MMA(ai, bj, At, Bt) do { __builtin_amdgcn_s_setprio(1); _Pragma("unroll") for (int m = 0; m < 4; ++m) _Pragma("unroll") for (int n = 0; n < 2; ++n) _Pragma("unroll") for (int k = 0; k < 2; ++k) \
;         acc[ai][bj][m][n] = __builtin_amdgcn_mfma_f32_16x16x32_bf16(Bt[n][k], At[m][k], acc[ai][bj][m][n], 0, 0, 0); __builtin_amdgcn_s_setprio(0); } while (0)
; #define PG8_WAIT_V(n) asm volatile("s_waitcnt vmcnt(" #n ")" ::: "memory")
; #define PG8_WAIT_L(n) asm volatile("s_waitcnt lgkmcnt(" #n ")" ::: "memory")
; #define PG8_BAR __builtin_amdgcn_s_barrier()
; #define PG8_SCHED __builtin_amdgcn_sched_barrier(0)
; template <class Epi, class Sched, bool ALIGN_EPI = false, bool SP2 = false>
; __device__ __forceinline__ void gemm_phase(PG8_LAS unsigned char* lds, const Gemm g, const Sched& S, const Epi& E, const int wave_) {
;     ...
;             PG8_LDA(At, 1, 1); PG8_STAGE(PG8_SB(1, 0), b3, voffB); PG8_STAGE(PG8_SB(1, 1), b3 + hstep, voffB); PG8_STAGE(PG8_SA(1, 0), a3, voffA);
;             PG8_WAIT_V(8); PG8_WAIT_L(0); PG8_BAR; PG8_MMA(1, 0, At, B0); PG8_MMA(1, 1, At, B1); PG8_BAR; PG8_SCHED;
	s_add_i32 s23, s23, s52
	v_lshl_add_u64 v[238:239], v[238:239], 0, s[34:35]
	s_mov_b32 m0, s23
	ds_read_b128 v[206:209], v203 offset:49152
	ds_read_b128 v[210:213], v203 offset:50176
	ds_read_b128 v[214:217], v203 offset:51200
	ds_read_b128 v[218:221], v203 offset:52224
	ds_read_b128 v[222:225], v203 offset:53248
	ds_read_b128 v[226:229], v203 offset:54272
	ds_read_b128 v[230:233], v203 offset:55296
	ds_read_b128 v[234:237], v203 offset:56320
	global_load_lds_dwordx4 v[238:239], off
	s_add_i32 m0, s23, 0x2000
	s_add_u32 s24, s48, 0x80080
	v_lshl_add_u64 v[238:239], v[240:241], 0, s[34:35]
	s_addc_u32 s25, s49, 0
	s_add_i32 s23, s86, s52
	global_load_lds_dwordx4 v[238:239], off
	v_lshl_add_u64 v[238:239], s[24:25], 0, v[130:131]
	s_mov_b32 m0, s23
	s_nop 0
	global_load_lds_dwordx4 v[238:239], off
	v_lshl_add_u64 v[238:239], s[24:25], 0, v[134:135]
	s_add_i32 m0, s23, 0x2000
	s_nop 0
	global_load_lds_dwordx4 v[238:239], off
	v_lshl_add_u64 v[238:239], v[242:243], 0, s[34:35]
	s_mov_b32 m0, s64
	s_nop 0
	global_load_lds_dwordx4 v[238:239], off
	v_lshl_add_u64 v[238:239], v[244:245], 0, s[34:35]
	s_mov_b32 m0, s65
	s_nop 0
	global_load_lds_dwordx4 v[238:239], off
	s_waitcnt vmcnt(8)
	s_waitcnt lgkmcnt(0)
	s_barrier
	s_setprio 1
	s_waitcnt lgkmcnt(0)
	v_mfma_f32_16x16x32_bf16 v[60:63], v[158:161], v[206:209], v[60:63]
	v_mfma_f32_16x16x32_bf16 v[52:55], v[166:169], v[206:209], v[52:55]
	v_mfma_f32_16x16x32_bf16 v[36:39], v[166:169], v[214:217], v[36:39]
	v_mfma_f32_16x16x32_bf16 v[44:47], v[158:161], v[214:217], v[44:47]
	v_mfma_f32_16x16x32_bf16 v[28:31], v[158:161], v[222:225], v[28:31]
	v_mfma_f32_16x16x32_bf16 v[20:23], v[166:169], v[222:225], v[20:23]
	v_mfma_f32_16x16x32_bf16 v[4:7], v[166:169], v[230:233], v[4:7]
	v_mfma_f32_16x16x32_bf16 v[12:15], v[158:161], v[230:233], v[12:15]
	v_mfma_f32_16x16x32_bf16 v[60:63], v[162:165], v[210:213], v[60:63]
	v_mfma_f32_16x16x32_bf16 v[52:55], v[170:173], v[210:213], v[52:55]
	v_mfma_f32_16x16x32_bf16 v[36:39], v[170:173], v[218:221], v[36:39]
	v_mfma_f32_16x16x32_bf16 v[44:47], v[162:165], v[218:221], v[44:47]
	v_mfma_f32_16x16x32_bf16 v[28:31], v[162:165], v[226:229], v[28:31]
	v_mfma_f32_16x16x32_bf16 v[20:23], v[170:173], v[226:229], v[20:23]
	v_mfma_f32_16x16x32_bf16 v[4:7], v[170:173], v[234:237], v[4:7]
	v_mfma_f32_16x16x32_bf16 v[12:15], v[162:165], v[234:237], v[12:15]
	s_setprio 0
	s_setprio 1
	v_mfma_f32_16x16x32_bf16 v[56:59], v[174:177], v[206:209], v[56:59]
	v_mfma_f32_16x16x32_bf16 v[48:51], v[182:185], v[206:209], v[48:51]
	v_mfma_f32_16x16x32_bf16 v[32:35], v[182:185], v[214:217], v[32:35]
	v_mfma_f32_16x16x32_bf16 v[40:43], v[174:177], v[214:217], v[40:43]
	v_mfma_f32_16x16x32_bf16 v[24:27], v[174:177], v[222:225], v[24:27]
	v_mfma_f32_16x16x32_bf16 v[16:19], v[182:185], v[222:225], v[16:19]
	v_mfma_f32_16x16x32_bf16 v[0:3], v[182:185], v[230:233], v[0:3]
	v_mfma_f32_16x16x32_bf16 v[8:11], v[174:177], v[230:233], v[8:11]
	v_mfma_f32_16x16x32_bf16 v[56:59], v[178:181], v[210:213], v[56:59]
	v_mfma_f32_16x16x32_bf16 v[48:51], v[186:189], v[210:213], v[48:51]
	v_mfma_f32_16x16x32_bf16 v[32:35], v[186:189], v[218:221], v[32:35]
	v_mfma_f32_16x16x32_bf16 v[40:43], v[178:181], v[218:221], v[40:43]
	v_mfma_f32_16x16x32_bf16 v[24:27], v[178:181], v[226:229], v[24:27]
	v_mfma_f32_16x16x32_bf16 v[16:19], v[186:189], v[226:229], v[16:19]
	v_mfma_f32_16x16x32_bf16 v[0:3], v[186:189], v[234:237], v[0:3]
	v_mfma_f32_16x16x32_bf16 v[8:11], v[178:181], v[234:237], v[8:11]
	s_setprio 0
	s_barrier
	s_add_i32 s22, s22, 2
	s_add_u32 s46, s46, 0x100
	s_addc_u32 s47, s47, 0
	s_add_u32 vcc_hi, vcc_hi, 0x100
	s_addc_u32 s97, s97, 0
	s_cmp_gt_u32 s22, 29
	s_cbranch_scc0 .LBB0_129
	s_and_b64 vcc, exec, s[74:75]
	s_cbranch_vccz .LBB0_132
	s_barrier

; #define PG8_STAGE(bufoff, gbase, voff) do { _Pragma("unroll") for (int _i = 0; _i < 2; ++_i) \
;         __builtin_amdgcn_global_load_lds((const unsigned*)((const char*)(gbase) + (voff)[_i]), (PG8_LAS unsigned*)(lds + (bufoff) + ldsw + _i * 8192), 16, 0, 0); } while (0)
; #define PG8_LDA(dst, b, h) do { _Pragma("unroll") for (int m = 0; m < 4; ++m) _Pragma("unroll") for (int k = 0; k < 2; ++k) dst[m][k] = *(const PG8_LAS bf16x8*)(lds + PG8_SA(b, h) + aoff + m * 2048 + k * 1024); } while (0)
; #define PG8_LDB(dst, b, h) do { _Pragma("unroll") for (int n = 0; n < 2; ++n) _Pragma("unroll") for (int k = 0; k < 2; ++k) dst[n][k] = *(const PG8_LAS bf16x8*)(lds + PG8_SB(b, h) + boff + n * 2048 + k * 1024); } while (0)
; #define PG8_MMA(ai, bj, At, Bt) do { __builtin_amdgcn_s_setprio(1); _Pragma("unroll") for (int m = 0; m < 4; ++m) _Pragma("unroll") for (int n = 0; n < 2; ++n) _Pragma("unroll") for (int k = 0; k < 2; ++k) \
;         acc[ai][bj][m][n] = __builtin_amdgcn_mfma_f32_16x16x32_bf16(Bt[n][k], At[m][k], acc[ai][bj][m][n], 0, 0, 0); __builtin_amdgcn_s_setprio(0); } while (0)
; #define PG8_WAIT_V(n) asm volatile("s_waitcnt vmcnt(" #n ")" ::: "memory")
; #define PG8_WAIT_L(n) asm volatile("s_waitcnt lgkmcnt(" #n ")" ::: "memory")
; #define PG8_BAR __builtin_amdgcn_s_barrier()
; #define PG8_SCHED __builtin_amdgcn_sched_barrier(0)
; template <class Epi, class Sched, bool ALIGN_EPI = false, bool SP2 = false>
; __device__ __forceinline__ void gemm_phase(PG8_LAS unsigned char* lds, const Gemm g, const Sched& S, const Epi& E, const int wave_) {
;     ...
;             PG8_LDB(B0, 0, 0); PG8_LDB(B1, 0, 1); PG8_SCHED; PG8_LDA(At, 0, 0); PG8_STAGE(PG8_SA(1, 1), a1 + hstep, voffA);
;             PG8_WAIT_V(8); PG8_WAIT_L(0); PG8_BAR; PG8_MMA(0, 0, At, B0); PG8_MMA(0, 1, At, B1); PG8_BAR; PG8_SCHED;
;             PG8_LDA(At, 0, 1); PG8_STAGE(PG8_SB(0, 0), b2, voffB); PG8_STAGE(PG8_SB(0, 1), b2 + hstep, voffB); PG8_STAGE(PG8_SA(0, 0), a2, voffA);
.LBB0_402:
	ds_read_b128 v[128:131], v189
	ds_read_b128 v[132:135], v189 offset:1024
	ds_read_b128 v[136:139], v189 offset:2048
	ds_read_b128 v[140:143], v189 offset:3072
	ds_read_b128 v[144:147], v201
	ds_read_b128 v[148:151], v201 offset:1024
	ds_read_b128 v[180:183], v201 offset:2048
	ds_read_b128 v[184:187], v201 offset:3072
	s_add_u32 s30, s28, 0xfff00080
	s_addc_u32 s31, s29, -1
	s_cmp_eq_u32 s53, 60
	s_cselect_b32 s35, s19, s31
	s_cselect_b32 s34, s25, s30
	s_cselect_b32 s31, s17, s52
	s_cselect_b32 s30, s50, s51
	v_lshl_add_u64 v[170:171], s[28:29], 0, v[162:163]
	s_add_i32 m0, s27, 0xc000
	ds_read_b128 v[190:193], v202
	ds_read_b128 v[196:199], v202 offset:1024
	ds_read_b128 v[204:207], v202 offset:2048
	ds_read_b128 v[208:211], v202 offset:3072
	ds_read_b128 v[212:215], v202 offset:4096
	ds_read_b128 v[216:219], v202 offset:5120
	ds_read_b128 v[220:223], v202 offset:6144
	ds_read_b128 v[224:227], v202 offset:7168
	global_load_lds_dwordx4 v[170:171], off
	v_lshl_add_u64 v[170:171], s[28:29], 0, v[164:165]
	s_add_i32 m0, s27, 0xe000
	s_nop 0
	global_load_lds_dwordx4 v[170:171], off
	s_waitcnt vmcnt(8)
	s_waitcnt lgkmcnt(0)
	s_barrier
	s_setprio 1
	s_waitcnt lgkmcnt(0)
	v_mfma_f32_16x16x32_bf16 v[124:127], v[128:131], v[190:193], v[124:127]
	v_mfma_f32_16x16x32_bf16 v[120:123], v[136:139], v[190:193], v[120:123]
	v_mfma_f32_16x16x32_bf16 v[104:107], v[136:139], v[204:207], v[104:107]
	v_mfma_f32_16x16x32_bf16 v[108:111], v[128:131], v[204:207], v[108:111]
	v_mfma_f32_16x16x32_bf16 v[92:95], v[128:131], v[212:215], v[92:95]
	v_mfma_f32_16x16x32_bf16 v[88:91], v[136:139], v[212:215], v[88:91]
	v_mfma_f32_16x16x32_bf16 v[72:75], v[136:139], v[220:223], v[72:75]
	v_mfma_f32_16x16x32_bf16 v[76:79], v[128:131], v[220:223], v[76:79]
	v_mfma_f32_16x16x32_bf16 v[124:127], v[132:135], v[196:199], v[124:127]
	v_mfma_f32_16x16x32_bf16 v[120:123], v[140:143], v[196:199], v[120:123]
	v_mfma_f32_16x16x32_bf16 v[104:107], v[140:143], v[208:211], v[104:107]
	v_mfma_f32_16x16x32_bf16 v[108:111], v[132:135], v[208:211], v[108:111]
	v_mfma_f32_16x16x32_bf16 v[92:95], v[132:135], v[216:219], v[92:95]
	v_mfma_f32_16x16x32_bf16 v[88:91], v[140:143], v[216:219], v[88:91]
	v_mfma_f32_16x16x32_bf16 v[72:75], v[140:143], v[224:227], v[72:75]
	v_mfma_f32_16x16x32_bf16 v[76:79], v[132:135], v[224:227], v[76:79]
	s_setprio 0
	s_setprio 1
	v_mfma_f32_16x16x32_bf16 v[116:119], v[144:147], v[190:193], v[116:119]
	v_mfma_f32_16x16x32_bf16 v[112:115], v[180:183], v[190:193], v[112:115]
	v_mfma_f32_16x16x32_bf16 v[96:99], v[180:183], v[204:207], v[96:99]
	v_mfma_f32_16x16x32_bf16 v[100:103], v[144:147], v[204:207], v[100:103]
	v_mfma_f32_16x16x32_bf16 v[84:87], v[144:147], v[212:215], v[84:87]
	v_mfma_f32_16x16x32_bf16 v[80:83], v[180:183], v[212:215], v[80:83]
	v_mfma_f32_16x16x32_bf16 v[64:67], v[180:183], v[220:223], v[64:67]
	v_mfma_f32_16x16x32_bf16 v[68:71], v[144:147], v[220:223], v[68:71]
	v_mfma_f32_16x16x32_bf16 v[116:119], v[148:151], v[196:199], v[116:119]
	v_mfma_f32_16x16x32_bf16 v[112:115], v[184:187], v[196:199], v[112:115]
	v_mfma_f32_16x16x32_bf16 v[96:99], v[184:187], v[208:211], v[96:99]
	v_mfma_f32_16x16x32_bf16 v[100:103], v[148:151], v[208:211], v[100:103]
	v_mfma_f32_16x16x32_bf16 v[84:87], v[148:151], v[216:219], v[84:87]
	v_mfma_f32_16x16x32_bf16 v[80:83], v[184:187], v[216:219], v[80:83]
	v_mfma_f32_16x16x32_bf16 v[64:67], v[184:187], v[224:227], v[64:67]
	v_mfma_f32_16x16x32_bf16 v[68:71], v[148:151], v[224:227], v[68:71]
	s_setprio 0
	s_barrier
	s_add_i32 s54, s48, s36
	v_lshl_add_u64 v[170:171], s[30:31], 0, v[156:157]
	s_mov_b32 m0, s54
	ds_read_b128 v[190:193], v202 offset:16384
	ds_read_b128 v[196:199], v202 offset:17408
	ds_read_b128 v[204:207], v202 offset:18432
	ds_read_b128 v[208:211], v202 offset:19456
	ds_read_b128 v[212:215], v202 offset:20480
	ds_read_b128 v[216:219], v202 offset:21504
	ds_read_b128 v[220:223], v202 offset:22528
	ds_read_b128 v[224:227], v202 offset:23552
	global_load_lds_dwordx4 v[170:171], off
	s_add_i32 m0, s54, 0x2000
	s_add_u32 s54, s30, 0x100000
	v_lshl_add_u64 v[228:229], s[30:31], 0, v[160:161]
	s_addc_u32 s55, s31, 0
	s_add_i32 s56, s49, s36
	global_load_lds_dwordx4 v[228:229], off
	v_lshl_add_u64 v[230:231], s[54:55], 0, v[156:157]
	s_mov_b32 m0, s56
	v_lshl_add_u64 v[232:233], s[34:35], 0, v[158:159]
	global_load_lds_dwordx4 v[230:231], off
	v_lshl_add_u64 v[230:231], s[54:55], 0, v[160:161]
	s_add_i32 m0, s56, 0x2000
	s_nop 0
	global_load_lds_dwordx4 v[230:231], off
	v_lshl_add_u64 v[230:231], s[34:35], 0, v[154:155]
	s_mov_b32 m0, s27
	s_nop 0
	global_load_lds_dwordx4 v[230:231], off
	s_mov_b32 m0, s37
	s_nop 0
	global_load_lds_dwordx4 v[232:233], off
	s_waitcnt vmcnt(8)
	s_waitcnt lgkmcnt(0)
	s_barrier
; #define PG8_STAGE(bufoff, gbase, voff) do { _Pragma("unroll") for (int _i = 0; _i < 2; ++_i) \
;         __builtin_amdgcn_global_load_lds((const unsigned*)((const char*)(gbase) + (voff)[_i]), (PG8_LAS unsigned*)(lds + (bufoff) + ldsw + _i * 8192), 16, 0, 0); } while (0)
; #define PG8_LDA(dst, b, h) do { _Pragma("unroll") for (int m = 0; m < 4; ++m) _Pragma("unroll") for (int k = 0; k < 2; ++k) dst[m][k] = *(const PG8_LAS bf16x8*)(lds + PG8_SA(b, h) + aoff + m * 2048 + k * 1024); } while (0)
; #define PG8_LDB(dst, b, h) do { _Pragma("unroll") for (int n = 0; n < 2; ++n) _Pragma("unroll") for (int k = 0; k < 2; ++k) dst[n][k] = *(const PG8_LAS bf16x8*)(lds + PG8_SB(b, h) + boff + n * 2048 + k * 1024); } while (0)
; #define PG8_MMA(ai, bj, At, Bt) do { __builtin_amdgcn_s_setprio(1); _Pragma("unroll") for (int m = 0; m < 4; ++m) _Pragma("unroll") for (int n = 0; n < 2; ++n) _Pragma("unroll") for (int k = 0; k < 2; ++k) \
;         acc[ai][bj][m][n] = __builtin_amdgcn_mfma_f32_16x16x32_bf16(Bt[n][k], At[m][k], acc[ai][bj][m][n], 0, 0, 0); __builtin_amdgcn_s_setprio(0); } while (0)
; #define PG8_WAIT_V(n) asm volatile("s_waitcnt vmcnt(" #n ")" ::: "memory")
; #define PG8_WAIT_L(n) asm volatile("s_waitcnt lgkmcnt(" #n ")" ::: "memory")
; #define PG8_BAR __builtin_amdgcn_s_barrier()
; #define PG8_SCHED __builtin_amdgcn_sched_barrier(0)
; template <class Epi, class Sched, bool ALIGN_EPI = false, bool SP2 = false>
; __device__ __forceinline__ void gemm_phase(PG8_LAS unsigned char* lds, const Gemm g, const Sched& S, const Epi& E, const int wave_) {
;     ...
;             PG8_WAIT_V(8); PG8_WAIT_L(0); PG8_BAR; PG8_MMA(1, 0, At, B0); PG8_MMA(1, 1, At, B1); PG8_BAR; PG8_SCHED;
;             PG8_LDB(B0, 1, 0); PG8_LDB(B1, 1, 1); PG8_SCHED; PG8_LDA(At, 1, 0); PG8_STAGE(PG8_SA(0, 1), a2 + hstep, voffA);
;             PG8_WAIT_V(8); PG8_WAIT_L(0); PG8_BAR; PG8_MMA(0, 0, At, B0); PG8_MMA(0, 1, At, B1); PG8_BAR; PG8_SCHED;
	s_setprio 1
	s_waitcnt lgkmcnt(0)
	v_mfma_f32_16x16x32_bf16 v[60:63], v[128:131], v[190:193], v[60:63]
	v_mfma_f32_16x16x32_bf16 v[56:59], v[136:139], v[190:193], v[56:59]
	v_mfma_f32_16x16x32_bf16 v[40:43], v[136:139], v[204:207], v[40:43]
	v_mfma_f32_16x16x32_bf16 v[44:47], v[128:131], v[204:207], v[44:47]
	v_mfma_f32_16x16x32_bf16 v[28:31], v[128:131], v[212:215], v[28:31]
	v_mfma_f32_16x16x32_bf16 v[24:27], v[136:139], v[212:215], v[24:27]
	v_mfma_f32_16x16x32_bf16 v[8:11], v[136:139], v[220:223], v[8:11]
	v_mfma_f32_16x16x32_bf16 v[12:15], v[128:131], v[220:223], v[12:15]
	v_mfma_f32_16x16x32_bf16 v[60:63], v[132:135], v[196:199], v[60:63]
	v_mfma_f32_16x16x32_bf16 v[56:59], v[140:143], v[196:199], v[56:59]
	v_mfma_f32_16x16x32_bf16 v[40:43], v[140:143], v[208:211], v[40:43]
	v_mfma_f32_16x16x32_bf16 v[44:47], v[132:135], v[208:211], v[44:47]
	v_mfma_f32_16x16x32_bf16 v[28:31], v[132:135], v[216:219], v[28:31]
	v_mfma_f32_16x16x32_bf16 v[24:27], v[140:143], v[216:219], v[24:27]
	v_mfma_f32_16x16x32_bf16 v[8:11], v[140:143], v[224:227], v[8:11]
	v_mfma_f32_16x16x32_bf16 v[12:15], v[132:135], v[224:227], v[12:15]
	s_setprio 0
	s_setprio 1
	v_mfma_f32_16x16x32_bf16 v[52:55], v[144:147], v[190:193], v[52:55]
	v_mfma_f32_16x16x32_bf16 v[48:51], v[180:183], v[190:193], v[48:51]
	v_mfma_f32_16x16x32_bf16 v[32:35], v[180:183], v[204:207], v[32:35]
	v_mfma_f32_16x16x32_bf16 v[36:39], v[144:147], v[204:207], v[36:39]
	v_mfma_f32_16x16x32_bf16 v[20:23], v[144:147], v[212:215], v[20:23]
	v_mfma_f32_16x16x32_bf16 v[16:19], v[180:183], v[212:215], v[16:19]
	v_mfma_f32_16x16x32_bf16 v[0:3], v[180:183], v[220:223], v[0:3]
	v_mfma_f32_16x16x32_bf16 v[4:7], v[144:147], v[220:223], v[4:7]
	v_mfma_f32_16x16x32_bf16 v[52:55], v[148:151], v[196:199], v[52:55]
	v_mfma_f32_16x16x32_bf16 v[48:51], v[184:187], v[196:199], v[48:51]
	v_mfma_f32_16x16x32_bf16 v[32:35], v[184:187], v[208:211], v[32:35]
	v_mfma_f32_16x16x32_bf16 v[36:39], v[148:151], v[208:211], v[36:39]
	v_mfma_f32_16x16x32_bf16 v[20:23], v[148:151], v[216:219], v[20:23]
	v_mfma_f32_16x16x32_bf16 v[16:19], v[184:187], v[216:219], v[16:19]
	v_mfma_f32_16x16x32_bf16 v[0:3], v[184:187], v[224:227], v[0:3]
	v_mfma_f32_16x16x32_bf16 v[4:7], v[148:151], v[224:227], v[4:7]
	s_setprio 0
	s_barrier
	s_add_i32 s54, 0, 0x18000
	s_add_i32 s55, 0, 0x1c000
	v_add_u32_e32 v140, s54, v173
	v_add_u32_e32 v172, s55, v173
	ds_read_b128 v[128:131], v140
	ds_read_b128 v[132:135], v140 offset:1024
	ds_read_b128 v[136:139], v140 offset:2048
	ds_read_b128 v[140:143], v140 offset:3072
	ds_read_b128 v[144:147], v172
	ds_read_b128 v[148:151], v172 offset:1024
	ds_read_b128 v[180:183], v172 offset:2048
	ds_read_b128 v[184:187], v172 offset:3072
	s_add_u32 s34, s34, 0x100000
	s_addc_u32 s35, s35, 0
	s_mov_b32 m0, s40
	v_lshl_add_u64 v[234:235], s[34:35], 0, v[154:155]
	ds_read_b128 v[190:193], v202 offset:32768
	ds_read_b128 v[196:199], v202 offset:33792
	ds_read_b128 v[204:207], v202 offset:34816
	ds_read_b128 v[208:211], v202 offset:35840
	ds_read_b128 v[212:215], v202 offset:36864
	ds_read_b128 v[216:219], v202 offset:37888
	ds_read_b128 v[220:223], v202 offset:38912
	ds_read_b128 v[224:227], v202 offset:39936
	global_load_lds_dwordx4 v[234:235], off
	v_lshl_add_u64 v[234:235], s[34:35], 0, v[158:159]
	s_mov_b32 m0, s41
	s_nop 0
	global_load_lds_dwordx4 v[234:235], off
	s_waitcnt vmcnt(8)
	s_waitcnt lgkmcnt(0)
	s_barrier
	s_setprio 1
	s_waitcnt lgkmcnt(0)
	v_mfma_f32_16x16x32_bf16 v[124:127], v[128:131], v[190:193], v[124:127]
	v_mfma_f32_16x16x32_bf16 v[120:123], v[136:139], v[190:193], v[120:123]
	v_mfma_f32_16x16x32_bf16 v[104:107], v[136:139], v[204:207], v[104:107]
	v_mfma_f32_16x16x32_bf16 v[108:111], v[128:131], v[204:207], v[108:111]
	v_mfma_f32_16x16x32_bf16 v[92:95], v[128:131], v[212:215], v[92:95]
	v_mfma_f32_16x16x32_bf16 v[88:91], v[136:139], v[212:215], v[88:91]
	v_mfma_f32_16x16x32_bf16 v[72:75], v[136:139], v[220:223], v[72:75]
	v_mfma_f32_16x16x32_bf16 v[76:79], v[128:131], v[220:223], v[76:79]
	v_mfma_f32_16x16x32_bf16 v[124:127], v[132:135], v[196:199], v[124:127]
	v_mfma_f32_16x16x32_bf16 v[120:123], v[140:143], v[196:199], v[120:123]
	v_mfma_f32_16x16x32_bf16 v[104:107], v[140:143], v[208:211], v[104:107]
	v_mfma_f32_16x16x32_bf16 v[108:111], v[132:135], v[208:211], v[108:111]
	v_mfma_f32_16x16x32_bf16 v[92:95], v[132:135], v[216:219], v[92:95]
	v_mfma_f32_16x16x32_bf16 v[88:91], v[140:143], v[216:219], v[88:91]
	v_mfma_f32_16x16x32_bf16 v[72:75], v[140:143], v[224:227], v[72:75]
	v_mfma_f32_16x16x32_bf16 v[76:79], v[132:135], v[224:227], v[76:79]
	s_setprio 0
	s_setprio 1
	v_mfma_f32_16x16x32_bf16 v[116:119], v[144:147], v[190:193], v[116:119]
	v_mfma_f32_16x16x32_bf16 v[112:115], v[180:183], v[190:193], v[112:115]
	v_mfma_f32_16x16x32_bf16 v[96:99], v[180:183], v[204:207], v[96:99]
	v_mfma_f32_16x16x32_bf16 v[100:103], v[144:147], v[204:207], v[100:103]
	v_mfma_f32_16x16x32_bf16 v[84:87], v[144:147], v[212:215], v[84:87]
	v_mfma_f32_16x16x32_bf16 v[80:83], v[180:183], v[212:215], v[80:83]
	v_mfma_f32_16x16x32_bf16 v[64:67], v[180:183], v[220:223], v[64:67]
	v_mfma_f32_16x16x32_bf16 v[68:71], v[144:147], v[220:223], v[68:71]
	v_mfma_f32_16x16x32_bf16 v[116:119], v[148:151], v[196:199], v[116:119]
	v_mfma_f32_16x16x32_bf16 v[112:115], v[184:187], v[196:199], v[112:115]
	v_mfma_f32_16x16x32_bf16 v[96:99], v[184:187], v[208:211], v[96:99]
	v_mfma_f32_16x16x32_bf16 v[100:103], v[148:151], v[208:211], v[100:103]
	v_mfma_f32_16x16x32_bf16 v[84:87], v[148:151], v[216:219], v[84:87]
	v_mfma_f32_16x16x32_bf16 v[80:83], v[184:187], v[216:219], v[80:83]
	v_mfma_f32_16x16x32_bf16 v[64:67], v[184:187], v[224:227], v[64:67]
	v_mfma_f32_16x16x32_bf16 v[68:71], v[148:151], v[224:227], v[68:71]
	s_setprio 0
	s_barrier
; #define PG8_STAGE(bufoff, gbase, voff) do { _Pragma("unroll") for (int _i = 0; _i < 2; ++_i) \
;         __builtin_amdgcn_global_load_lds((const unsigned*)((const char*)(gbase) + (voff)[_i]), (PG8_LAS unsigned*)(lds + (bufoff) + ldsw + _i * 8192), 16, 0, 0); } while (0)
; #define PG8_LDA(dst, b, h) do { _Pragma("unroll") for (int m = 0; m < 4; ++m) _Pragma("unroll") for (int k = 0; k < 2; ++k) dst[m][k] = *(const PG8_LAS bf16x8*)(lds + PG8_SA(b, h) + aoff + m * 2048 + k * 1024); } while (0)
; #define PG8_MMA(ai, bj, At, Bt) do { __builtin_amdgcn_s_setprio(1); _Pragma("unroll") for (int m = 0; m < 4; ++m) _Pragma("unroll") for (int n = 0; n < 2; ++n) _Pragma("unroll") for (int k = 0; k < 2; ++k) \
;         acc[ai][bj][m][n] = __builtin_amdgcn_mfma_f32_16x16x32_bf16(Bt[n][k], At[m][k], acc[ai][bj][m][n], 0, 0, 0); __builtin_amdgcn_s_setprio(0); } while (0)
; #define PG8_WAIT_V(n) asm volatile("s_waitcnt vmcnt(" #n ")" ::: "memory")
; #define PG8_WAIT_L(n) asm volatile("s_waitcnt lgkmcnt(" #n ")" ::: "memory")
; #define PG8_BAR __builtin_amdgcn_s_barrier()
; #define PG8_SCHED __builtin_amdgcn_sched_barrier(0)
; template <class Epi, class Sched, bool ALIGN_EPI = false, bool SP2 = false>
; __device__ __forceinline__ void gemm_phase(PG8_LAS unsigned char* lds, const Gemm g, const Sched& S, const Epi& E, const int wave_) {
;     ...
;             PG8_LDA(At, 1, 1); PG8_STAGE(PG8_SB(1, 0), b3, voffB); PG8_STAGE(PG8_SB(1, 1), b3 + hstep, voffB); PG8_STAGE(PG8_SA(1, 0), a3, voffA);
;             PG8_WAIT_V(8); PG8_WAIT_L(0); PG8_BAR; PG8_MMA(1, 0, At, B0); PG8_MMA(1, 1, At, B1); PG8_BAR; PG8_SCHED;
	s_add_i32 s34, s54, s36
	v_lshl_add_u64 v[170:171], v[170:171], 0, s[14:15]
	s_mov_b32 m0, s34
	ds_read_b128 v[190:193], v202 offset:49152
	ds_read_b128 v[196:199], v202 offset:50176
	ds_read_b128 v[204:207], v202 offset:51200
	ds_read_b128 v[208:211], v202 offset:52224
	ds_read_b128 v[212:215], v202 offset:53248
	ds_read_b128 v[216:219], v202 offset:54272
	ds_read_b128 v[220:223], v202 offset:55296
	ds_read_b128 v[224:227], v202 offset:56320
	global_load_lds_dwordx4 v[170:171], off
	s_add_i32 m0, s34, 0x2000
	s_add_u32 s30, s30, 0x100080
	v_lshl_add_u64 v[170:171], v[228:229], 0, s[14:15]
	s_addc_u32 s31, s31, 0
	s_add_i32 s34, s55, s36
	global_load_lds_dwordx4 v[170:171], off
	v_lshl_add_u64 v[170:171], s[30:31], 0, v[156:157]
	s_mov_b32 m0, s34
	s_nop 0
	global_load_lds_dwordx4 v[170:171], off
	v_lshl_add_u64 v[170:171], s[30:31], 0, v[160:161]
	s_add_i32 m0, s34, 0x2000
	s_nop 0
	global_load_lds_dwordx4 v[170:171], off
	v_lshl_add_u64 v[170:171], v[230:231], 0, s[14:15]
	s_mov_b32 m0, s45
	s_nop 0
	global_load_lds_dwordx4 v[170:171], off
	v_lshl_add_u64 v[170:171], v[232:233], 0, s[14:15]
	s_mov_b32 m0, s46
	s_nop 0
	global_load_lds_dwordx4 v[170:171], off
	s_waitcnt vmcnt(8)
	s_waitcnt lgkmcnt(0)
	s_barrier
	s_setprio 1
	s_waitcnt lgkmcnt(0)
	v_mfma_f32_16x16x32_bf16 v[60:63], v[128:131], v[190:193], v[60:63]
	v_mfma_f32_16x16x32_bf16 v[56:59], v[136:139], v[190:193], v[56:59]
	v_mfma_f32_16x16x32_bf16 v[40:43], v[136:139], v[204:207], v[40:43]
	v_mfma_f32_16x16x32_bf16 v[44:47], v[128:131], v[204:207], v[44:47]
	v_mfma_f32_16x16x32_bf16 v[28:31], v[128:131], v[212:215], v[28:31]
	v_mfma_f32_16x16x32_bf16 v[24:27], v[136:139], v[212:215], v[24:27]
	v_mfma_f32_16x16x32_bf16 v[8:11], v[136:139], v[220:223], v[8:11]
	v_mfma_f32_16x16x32_bf16 v[12:15], v[128:131], v[220:223], v[12:15]
	v_mfma_f32_16x16x32_bf16 v[60:63], v[132:135], v[196:199], v[60:63]
	v_mfma_f32_16x16x32_bf16 v[56:59], v[140:143], v[196:199], v[56:59]
	v_mfma_f32_16x16x32_bf16 v[40:43], v[140:143], v[208:211], v[40:43]
	v_mfma_f32_16x16x32_bf16 v[44:47], v[132:135], v[208:211], v[44:47]
	v_mfma_f32_16x16x32_bf16 v[28:31], v[132:135], v[216:219], v[28:31]
	v_mfma_f32_16x16x32_bf16 v[24:27], v[140:143], v[216:219], v[24:27]
	v_mfma_f32_16x16x32_bf16 v[8:11], v[140:143], v[224:227], v[8:11]
	v_mfma_f32_16x16x32_bf16 v[12:15], v[132:135], v[224:227], v[12:15]
	s_setprio 0
	s_setprio 1
	v_mfma_f32_16x16x32_bf16 v[52:55], v[144:147], v[190:193], v[52:55]
	v_mfma_f32_16x16x32_bf16 v[48:51], v[180:183], v[190:193], v[48:51]
	v_mfma_f32_16x16x32_bf16 v[32:35], v[180:183], v[204:207], v[32:35]
	v_mfma_f32_16x16x32_bf16 v[36:39], v[144:147], v[204:207], v[36:39]
	v_mfma_f32_16x16x32_bf16 v[20:23], v[144:147], v[212:215], v[20:23]
	v_mfma_f32_16x16x32_bf16 v[16:19], v[180:183], v[212:215], v[16:19]
	v_mfma_f32_16x16x32_bf16 v[0:3], v[180:183], v[220:223], v[0:3]
	v_mfma_f32_16x16x32_bf16 v[4:7], v[144:147], v[220:223], v[4:7]
	v_mfma_f32_16x16x32_bf16 v[52:55], v[148:151], v[196:199], v[52:55]
	v_mfma_f32_16x16x32_bf16 v[48:51], v[184:187], v[196:199], v[48:51]
	v_mfma_f32_16x16x32_bf16 v[32:35], v[184:187], v[208:211], v[32:35]
	v_mfma_f32_16x16x32_bf16 v[36:39], v[148:151], v[208:211], v[36:39]
	v_mfma_f32_16x16x32_bf16 v[20:23], v[148:151], v[216:219], v[20:23]
	v_mfma_f32_16x16x32_bf16 v[16:19], v[184:187], v[216:219], v[16:19]
	v_mfma_f32_16x16x32_bf16 v[0:3], v[184:187], v[224:227], v[0:3]
	v_mfma_f32_16x16x32_bf16 v[4:7], v[148:151], v[224:227], v[4:7]
	s_setprio 0
	s_barrier
	s_add_i32 s53, s53, 2
	s_add_u32 s28, s28, 0x100
	s_addc_u32 s29, s29, 0
	s_add_u32 s51, s51, 0x100
	s_addc_u32 s52, s52, 0
	s_cmp_gt_u32 s53, 61
	s_cbranch_scc0 .LBB0_402
	s_and_b64 vcc, exec, s[12:13]
	s_cbranch_vccz .LBB0_405
	s_barrier

; #define PG8_STAGE(bufoff, gbase, voff) do { _Pragma("unroll") for (int _i = 0; _i < 2; ++_i) \
;         __builtin_amdgcn_global_load_lds((const unsigned*)((const char*)(gbase) + (voff)[_i]), (PG8_LAS unsigned*)(lds + (bufoff) + ldsw + _i * 8192), 16, 0, 0); } while (0)
; #define PG8_LDA(dst, b, h) do { _Pragma("unroll") for (int m = 0; m < 4; ++m) _Pragma("unroll") for (int k = 0; k < 2; ++k) dst[m][k] = *(const PG8_LAS bf16x8*)(lds + PG8_SA(b, h) + aoff + m * 2048 + k * 1024); } while (0)
; #define PG8_LDB(dst, b, h) do { _Pragma("unroll") for (int n = 0; n < 2; ++n) _Pragma("unroll") for (int k = 0; k < 2; ++k) dst[n][k] = *(const PG8_LAS bf16x8*)(lds + PG8_SB(b, h) + boff + n * 2048 + k * 1024); } while (0)
; #define PG8_MMA(ai, bj, At, Bt) do { __builtin_amdgcn_s_setprio(1); _Pragma("unroll") for (int m = 0; m < 4; ++m) _Pragma("unroll") for (int n = 0; n < 2; ++n) _Pragma("unroll") for (int k = 0; k < 2; ++k) \
;         acc[ai][bj][m][n] = __builtin_amdgcn_mfma_f32_16x16x32_bf16(Bt[n][k], At[m][k], acc[ai][bj][m][n], 0, 0, 0); __builtin_amdgcn_s_setprio(0); } while (0)
; #define PG8_WAIT_V(n) asm volatile("s_waitcnt vmcnt(" #n ")" ::: "memory")
; #define PG8_WAIT_L(n) asm volatile("s_waitcnt lgkmcnt(" #n ")" ::: "memory")
; #define PG8_BAR __builtin_amdgcn_s_barrier()
; #define PG8_SCHED __builtin_amdgcn_sched_barrier(0)
; template <class Epi, class Sched, bool ALIGN_EPI = false, bool SP2 = false>
; __device__ __forceinline__ void gemm_phase(PG8_LAS unsigned char* lds, const Gemm g, const Sched& S, const Epi& E, const int wave_) {
;     ...
;             PG8_LDB(B0, 0, 0); PG8_LDB(B1, 0, 1); PG8_SCHED; PG8_LDA(At, 0, 0); PG8_STAGE(PG8_SA(1, 1), a1 + hstep, voffA);
;             PG8_WAIT_V(8); PG8_WAIT_L(0); PG8_BAR; PG8_MMA(0, 0, At, B0); PG8_MMA(0, 1, At, B1); PG8_BAR; PG8_SCHED;
;             PG8_LDA(At, 0, 1); PG8_STAGE(PG8_SB(0, 0), b2, voffB); PG8_STAGE(PG8_SB(0, 1), b2 + hstep, voffB); PG8_STAGE(PG8_SA(0, 0), a2, voffA);
.LBB0_495:
	ds_read_b128 v[146:149], v164
	ds_read_b128 v[154:157], v164 offset:1024
	ds_read_b128 v[158:161], v164 offset:2048
	ds_read_b128 v[168:171], v164 offset:3072
	ds_read_b128 v[172:175], v165
	ds_read_b128 v[176:179], v165 offset:1024
	ds_read_b128 v[180:183], v165 offset:2048
	ds_read_b128 v[184:187], v165 offset:3072
	s_add_u32 s40, s36, 0xfff80080
	s_addc_u32 s41, s37, -1
	s_cmp_eq_u32 s63, 28
	s_cselect_b32 s43, s5, s41
	s_cselect_b32 s42, s7, s40
	s_cselect_b32 s41, s27, s62
	s_cselect_b32 s40, s29, s61
	v_lshl_add_u64 v[150:151], s[36:37], 0, v[138:139]
	s_add_i32 m0, s45, 0xc000
	ds_read_b128 v[188:191], v166
	ds_read_b128 v[196:199], v166 offset:1024
	ds_read_b128 v[200:203], v166 offset:2048
	ds_read_b128 v[204:207], v166 offset:3072
	ds_read_b128 v[208:211], v166 offset:4096
	ds_read_b128 v[212:215], v166 offset:5120
	ds_read_b128 v[216:219], v166 offset:6144
	ds_read_b128 v[220:223], v166 offset:7168
	global_load_lds_dwordx4 v[150:151], off
	v_lshl_add_u64 v[150:151], s[36:37], 0, v[140:141]
	s_add_i32 m0, s45, 0xe000
	s_nop 0
	global_load_lds_dwordx4 v[150:151], off
	s_waitcnt vmcnt(8)
	s_waitcnt lgkmcnt(0)
	s_barrier
	s_setprio 1
	s_waitcnt lgkmcnt(0)
	v_mfma_f32_16x16x32_bf16 v[124:127], v[146:149], v[188:191], v[124:127]
	v_mfma_f32_16x16x32_bf16 v[120:123], v[158:161], v[188:191], v[120:123]
	v_mfma_f32_16x16x32_bf16 v[104:107], v[158:161], v[200:203], v[104:107]
	v_mfma_f32_16x16x32_bf16 v[108:111], v[146:149], v[200:203], v[108:111]
	v_mfma_f32_16x16x32_bf16 v[92:95], v[146:149], v[208:211], v[92:95]
	v_mfma_f32_16x16x32_bf16 v[88:91], v[158:161], v[208:211], v[88:91]
	v_mfma_f32_16x16x32_bf16 v[72:75], v[158:161], v[216:219], v[72:75]
	v_mfma_f32_16x16x32_bf16 v[76:79], v[146:149], v[216:219], v[76:79]
	v_mfma_f32_16x16x32_bf16 v[124:127], v[154:157], v[196:199], v[124:127]
	v_mfma_f32_16x16x32_bf16 v[120:123], v[168:171], v[196:199], v[120:123]
	v_mfma_f32_16x16x32_bf16 v[104:107], v[168:171], v[204:207], v[104:107]
	v_mfma_f32_16x16x32_bf16 v[108:111], v[154:157], v[204:207], v[108:111]
	v_mfma_f32_16x16x32_bf16 v[92:95], v[154:157], v[212:215], v[92:95]
	v_mfma_f32_16x16x32_bf16 v[88:91], v[168:171], v[212:215], v[88:91]
	v_mfma_f32_16x16x32_bf16 v[72:75], v[168:171], v[220:223], v[72:75]
	v_mfma_f32_16x16x32_bf16 v[76:79], v[154:157], v[220:223], v[76:79]
	s_setprio 0
	s_setprio 1
	v_mfma_f32_16x16x32_bf16 v[116:119], v[172:175], v[188:191], v[116:119]
	v_mfma_f32_16x16x32_bf16 v[112:115], v[180:183], v[188:191], v[112:115]
	v_mfma_f32_16x16x32_bf16 v[96:99], v[180:183], v[200:203], v[96:99]
	v_mfma_f32_16x16x32_bf16 v[100:103], v[172:175], v[200:203], v[100:103]
	v_mfma_f32_16x16x32_bf16 v[84:87], v[172:175], v[208:211], v[84:87]
	v_mfma_f32_16x16x32_bf16 v[80:83], v[180:183], v[208:211], v[80:83]
	v_mfma_f32_16x16x32_bf16 v[64:67], v[180:183], v[216:219], v[64:67]
	v_mfma_f32_16x16x32_bf16 v[68:71], v[172:175], v[216:219], v[68:71]
	v_mfma_f32_16x16x32_bf16 v[116:119], v[176:179], v[196:199], v[116:119]
	v_mfma_f32_16x16x32_bf16 v[112:115], v[184:187], v[196:199], v[112:115]
	v_mfma_f32_16x16x32_bf16 v[96:99], v[184:187], v[204:207], v[96:99]
	v_mfma_f32_16x16x32_bf16 v[100:103], v[176:179], v[204:207], v[100:103]
	v_mfma_f32_16x16x32_bf16 v[84:87], v[176:179], v[212:215], v[84:87]
	v_mfma_f32_16x16x32_bf16 v[80:83], v[184:187], v[212:215], v[80:83]
	v_mfma_f32_16x16x32_bf16 v[64:67], v[184:187], v[220:223], v[64:67]
	v_mfma_f32_16x16x32_bf16 v[68:71], v[176:179], v[220:223], v[68:71]
	s_setprio 0
	s_barrier
	s_add_i32 s64, s55, s44
	v_lshl_add_u64 v[150:151], s[40:41], 0, v[130:131]
	s_mov_b32 m0, s64
	ds_read_b128 v[188:191], v166 offset:16384
	ds_read_b128 v[196:199], v166 offset:17408
	ds_read_b128 v[200:203], v166 offset:18432
	ds_read_b128 v[204:207], v166 offset:19456
	ds_read_b128 v[208:211], v166 offset:20480
	ds_read_b128 v[212:215], v166 offset:21504
	ds_read_b128 v[216:219], v166 offset:22528
	ds_read_b128 v[220:223], v166 offset:23552
	global_load_lds_dwordx4 v[150:151], off
	s_add_i32 m0, s64, 0x2000
	s_add_u32 s64, s40, 0x80000
	v_lshl_add_u64 v[192:193], s[40:41], 0, v[134:135]
	s_addc_u32 s65, s41, 0
	s_add_i32 s66, s56, s44
	global_load_lds_dwordx4 v[192:193], off
	v_lshl_add_u64 v[224:225], s[64:65], 0, v[130:131]
	s_mov_b32 m0, s66
	v_lshl_add_u64 v[226:227], s[42:43], 0, v[132:133]
	global_load_lds_dwordx4 v[224:225], off
	v_lshl_add_u64 v[224:225], s[64:65], 0, v[134:135]
	s_add_i32 m0, s66, 0x2000
	s_nop 0
	global_load_lds_dwordx4 v[224:225], off
	v_lshl_add_u64 v[224:225], s[42:43], 0, v[128:129]
	s_mov_b32 m0, s45
	s_nop 0
	global_load_lds_dwordx4 v[224:225], off
	s_mov_b32 m0, s46
	s_nop 0
	global_load_lds_dwordx4 v[226:227], off
	s_waitcnt vmcnt(8)
	s_waitcnt lgkmcnt(0)
	s_barrier
; #define PG8_STAGE(bufoff, gbase, voff) do { _Pragma("unroll") for (int _i = 0; _i < 2; ++_i) \
;         __builtin_amdgcn_global_load_lds((const unsigned*)((const char*)(gbase) + (voff)[_i]), (PG8_LAS unsigned*)(lds + (bufoff) + ldsw + _i * 8192), 16, 0, 0); } while (0)
; #define PG8_LDA(dst, b, h) do { _Pragma("unroll") for (int m = 0; m < 4; ++m) _Pragma("unroll") for (int k = 0; k < 2; ++k) dst[m][k] = *(const PG8_LAS bf16x8*)(lds + PG8_SA(b, h) + aoff + m * 2048 + k * 1024); } while (0)
; #define PG8_LDB(dst, b, h) do { _Pragma("unroll") for (int n = 0; n < 2; ++n) _Pragma("unroll") for (int k = 0; k < 2; ++k) dst[n][k] = *(const PG8_LAS bf16x8*)(lds + PG8_SB(b, h) + boff + n * 2048 + k * 1024); } while (0)
; #define PG8_MMA(ai, bj, At, Bt) do { __builtin_amdgcn_s_setprio(1); _Pragma("unroll") for (int m = 0; m < 4; ++m) _Pragma("unroll") for (int n = 0; n < 2; ++n) _Pragma("unroll") for (int k = 0; k < 2; ++k) \
;         acc[ai][bj][m][n] = __builtin_amdgcn_mfma_f32_16x16x32_bf16(Bt[n][k], At[m][k], acc[ai][bj][m][n], 0, 0, 0); __builtin_amdgcn_s_setprio(0); } while (0)
; #define PG8_WAIT_V(n) asm volatile("s_waitcnt vmcnt(" #n ")" ::: "memory")
; #define PG8_WAIT_L(n) asm volatile("s_waitcnt lgkmcnt(" #n ")" ::: "memory")
; #define PG8_BAR __builtin_amdgcn_s_barrier()
; #define PG8_SCHED __builtin_amdgcn_sched_barrier(0)
; template <class Epi, class Sched, bool ALIGN_EPI = false, bool SP2 = false>
; __device__ __forceinline__ void gemm_phase(PG8_LAS unsigned char* lds, const Gemm g, const Sched& S, const Epi& E, const int wave_) {
;     ...
;             PG8_WAIT_V(8); PG8_WAIT_L(0); PG8_BAR; PG8_MMA(1, 0, At, B0); PG8_MMA(1, 1, At, B1); PG8_BAR; PG8_SCHED;
;             PG8_LDB(B0, 1, 0); PG8_LDB(B1, 1, 1); PG8_SCHED; PG8_LDA(At, 1, 0); PG8_STAGE(PG8_SA(0, 1), a2 + hstep, voffA);
;             PG8_WAIT_V(8); PG8_WAIT_L(0); PG8_BAR; PG8_MMA(0, 0, At, B0); PG8_MMA(0, 1, At, B1); PG8_BAR; PG8_SCHED;
	s_setprio 1
	s_waitcnt lgkmcnt(0)
	v_mfma_f32_16x16x32_bf16 v[60:63], v[146:149], v[188:191], v[60:63]
	v_mfma_f32_16x16x32_bf16 v[56:59], v[158:161], v[188:191], v[56:59]
	v_mfma_f32_16x16x32_bf16 v[40:43], v[158:161], v[200:203], v[40:43]
	v_mfma_f32_16x16x32_bf16 v[44:47], v[146:149], v[200:203], v[44:47]
	v_mfma_f32_16x16x32_bf16 v[28:31], v[146:149], v[208:211], v[28:31]
	v_mfma_f32_16x16x32_bf16 v[24:27], v[158:161], v[208:211], v[24:27]
	v_mfma_f32_16x16x32_bf16 v[8:11], v[158:161], v[216:219], v[8:11]
	v_mfma_f32_16x16x32_bf16 v[12:15], v[146:149], v[216:219], v[12:15]
	v_mfma_f32_16x16x32_bf16 v[60:63], v[154:157], v[196:199], v[60:63]
	v_mfma_f32_16x16x32_bf16 v[56:59], v[168:171], v[196:199], v[56:59]
	v_mfma_f32_16x16x32_bf16 v[40:43], v[168:171], v[204:207], v[40:43]
	v_mfma_f32_16x16x32_bf16 v[44:47], v[154:157], v[204:207], v[44:47]
	v_mfma_f32_16x16x32_bf16 v[28:31], v[154:157], v[212:215], v[28:31]
	v_mfma_f32_16x16x32_bf16 v[24:27], v[168:171], v[212:215], v[24:27]
	v_mfma_f32_16x16x32_bf16 v[8:11], v[168:171], v[220:223], v[8:11]
	v_mfma_f32_16x16x32_bf16 v[12:15], v[154:157], v[220:223], v[12:15]
	s_setprio 0
	s_setprio 1
	v_mfma_f32_16x16x32_bf16 v[52:55], v[172:175], v[188:191], v[52:55]
	v_mfma_f32_16x16x32_bf16 v[48:51], v[180:183], v[188:191], v[48:51]
	v_mfma_f32_16x16x32_bf16 v[32:35], v[180:183], v[200:203], v[32:35]
	v_mfma_f32_16x16x32_bf16 v[36:39], v[172:175], v[200:203], v[36:39]
	v_mfma_f32_16x16x32_bf16 v[20:23], v[172:175], v[208:211], v[20:23]
	v_mfma_f32_16x16x32_bf16 v[16:19], v[180:183], v[208:211], v[16:19]
	v_mfma_f32_16x16x32_bf16 v[0:3], v[180:183], v[216:219], v[0:3]
	v_mfma_f32_16x16x32_bf16 v[4:7], v[172:175], v[216:219], v[4:7]
	v_mfma_f32_16x16x32_bf16 v[52:55], v[176:179], v[196:199], v[52:55]
	v_mfma_f32_16x16x32_bf16 v[48:51], v[184:187], v[196:199], v[48:51]
	v_mfma_f32_16x16x32_bf16 v[32:35], v[184:187], v[204:207], v[32:35]
	v_mfma_f32_16x16x32_bf16 v[36:39], v[176:179], v[204:207], v[36:39]
	v_mfma_f32_16x16x32_bf16 v[20:23], v[176:179], v[212:215], v[20:23]
	v_mfma_f32_16x16x32_bf16 v[16:19], v[184:187], v[212:215], v[16:19]
	v_mfma_f32_16x16x32_bf16 v[0:3], v[184:187], v[220:223], v[0:3]
	v_mfma_f32_16x16x32_bf16 v[4:7], v[176:179], v[220:223], v[4:7]
	s_setprio 0
	s_barrier
	s_add_i32 s64, 0, 0x18000
	v_add_u32_e32 v136, s64, v162
	s_add_i32 s65, 0, 0x1c000
	ds_read_b128 v[146:149], v136
	ds_read_b128 v[154:157], v136 offset:1024
	ds_read_b128 v[158:161], v136 offset:2048
	ds_read_b128 v[168:171], v136 offset:3072
	v_add_u32_e32 v136, s65, v162
	ds_read_b128 v[172:175], v136
	ds_read_b128 v[176:179], v136 offset:1024
	ds_read_b128 v[180:183], v136 offset:2048
	ds_read_b128 v[184:187], v136 offset:3072
	s_add_u32 s42, s42, 0x80000
	s_addc_u32 s43, s43, 0
	s_mov_b32 m0, s47
	v_lshl_add_u64 v[228:229], s[42:43], 0, v[128:129]
	ds_read_b128 v[188:191], v166 offset:32768
	ds_read_b128 v[196:199], v166 offset:33792
	ds_read_b128 v[200:203], v166 offset:34816
	ds_read_b128 v[204:207], v166 offset:35840
	ds_read_b128 v[208:211], v166 offset:36864
	ds_read_b128 v[212:215], v166 offset:37888
	ds_read_b128 v[216:219], v166 offset:38912
	ds_read_b128 v[220:223], v166 offset:39936
	global_load_lds_dwordx4 v[228:229], off
	v_lshl_add_u64 v[228:229], s[42:43], 0, v[132:133]
	s_mov_b32 m0, s48
	s_nop 0
	global_load_lds_dwordx4 v[228:229], off
	s_waitcnt vmcnt(8)
	s_waitcnt lgkmcnt(0)
	s_barrier
	s_setprio 1
	s_waitcnt lgkmcnt(0)
	v_mfma_f32_16x16x32_bf16 v[124:127], v[146:149], v[188:191], v[124:127]
	v_mfma_f32_16x16x32_bf16 v[120:123], v[158:161], v[188:191], v[120:123]
	v_mfma_f32_16x16x32_bf16 v[104:107], v[158:161], v[200:203], v[104:107]
	v_mfma_f32_16x16x32_bf16 v[108:111], v[146:149], v[200:203], v[108:111]
	v_mfma_f32_16x16x32_bf16 v[92:95], v[146:149], v[208:211], v[92:95]
	v_mfma_f32_16x16x32_bf16 v[88:91], v[158:161], v[208:211], v[88:91]
	v_mfma_f32_16x16x32_bf16 v[72:75], v[158:161], v[216:219], v[72:75]
	v_mfma_f32_16x16x32_bf16 v[76:79], v[146:149], v[216:219], v[76:79]
	v_mfma_f32_16x16x32_bf16 v[124:127], v[154:157], v[196:199], v[124:127]
	v_mfma_f32_16x16x32_bf16 v[120:123], v[168:171], v[196:199], v[120:123]
	v_mfma_f32_16x16x32_bf16 v[104:107], v[168:171], v[204:207], v[104:107]
	v_mfma_f32_16x16x32_bf16 v[108:111], v[154:157], v[204:207], v[108:111]
	v_mfma_f32_16x16x32_bf16 v[92:95], v[154:157], v[212:215], v[92:95]
	v_mfma_f32_16x16x32_bf16 v[88:91], v[168:171], v[212:215], v[88:91]
	v_mfma_f32_16x16x32_bf16 v[72:75], v[168:171], v[220:223], v[72:75]
	v_mfma_f32_16x16x32_bf16 v[76:79], v[154:157], v[220:223], v[76:79]
	s_setprio 0
	s_setprio 1
	v_mfma_f32_16x16x32_bf16 v[116:119], v[172:175], v[188:191], v[116:119]
	v_mfma_f32_16x16x32_bf16 v[112:115], v[180:183], v[188:191], v[112:115]
	v_mfma_f32_16x16x32_bf16 v[96:99], v[180:183], v[200:203], v[96:99]
	v_mfma_f32_16x16x32_bf16 v[100:103], v[172:175], v[200:203], v[100:103]
	v_mfma_f32_16x16x32_bf16 v[84:87], v[172:175], v[208:211], v[84:87]
	v_mfma_f32_16x16x32_bf16 v[80:83], v[180:183], v[208:211], v[80:83]
	v_mfma_f32_16x16x32_bf16 v[64:67], v[180:183], v[216:219], v[64:67]
	v_mfma_f32_16x16x32_bf16 v[68:71], v[172:175], v[216:219], v[68:71]
	v_mfma_f32_16x16x32_bf16 v[116:119], v[176:179], v[196:199], v[116:119]
	v_mfma_f32_16x16x32_bf16 v[112:115], v[184:187], v[196:199], v[112:115]
	v_mfma_f32_16x16x32_bf16 v[96:99], v[184:187], v[204:207], v[96:99]
	v_mfma_f32_16x16x32_bf16 v[100:103], v[176:179], v[204:207], v[100:103]
	v_mfma_f32_16x16x32_bf16 v[84:87], v[176:179], v[212:215], v[84:87]
	v_mfma_f32_16x16x32_bf16 v[80:83], v[184:187], v[212:215], v[80:83]
	v_mfma_f32_16x16x32_bf16 v[64:67], v[184:187], v[220:223], v[64:67]
	v_mfma_f32_16x16x32_bf16 v[68:71], v[176:179], v[220:223], v[68:71]
	s_setprio 0
	s_barrier
; #define PG8_STAGE(bufoff, gbase, voff) do { _Pragma("unroll") for (int _i = 0; _i < 2; ++_i) \
;         __builtin_amdgcn_global_load_lds((const unsigned*)((const char*)(gbase) + (voff)[_i]), (PG8_LAS unsigned*)(lds + (bufoff) + ldsw + _i * 8192), 16, 0, 0); } while (0)
; #define PG8_LDA(dst, b, h) do { _Pragma("unroll") for (int m = 0; m < 4; ++m) _Pragma("unroll") for (int k = 0; k < 2; ++k) dst[m][k] = *(const PG8_LAS bf16x8*)(lds + PG8_SA(b, h) + aoff + m * 2048 + k * 1024); } while (0)
; #define PG8_MMA(ai, bj, At, Bt) do { __builtin_amdgcn_s_setprio(1); _Pragma("unroll") for (int m = 0; m < 4; ++m) _Pragma("unroll") for (int n = 0; n < 2; ++n) _Pragma("unroll") for (int k = 0; k < 2; ++k) \
;         acc[ai][bj][m][n] = __builtin_amdgcn_mfma_f32_16x16x32_bf16(Bt[n][k], At[m][k], acc[ai][bj][m][n], 0, 0, 0); __builtin_amdgcn_s_setprio(0); } while (0)
; #define PG8_WAIT_V(n) asm volatile("s_waitcnt vmcnt(" #n ")" ::: "memory")
; #define PG8_WAIT_L(n) asm volatile("s_waitcnt lgkmcnt(" #n ")" ::: "memory")
; #define PG8_BAR __builtin_amdgcn_s_barrier()
; #define PG8_SCHED __builtin_amdgcn_sched_barrier(0)
; template <class Epi, class Sched, bool ALIGN_EPI = false, bool SP2 = false>
; __device__ __forceinline__ void gemm_phase(PG8_LAS unsigned char* lds, const Gemm g, const Sched& S, const Epi& E, const int wave_) {
;     ...
;         for (int t = 0; t < nt; t += 2) {
;             const bool last = (t == nt - 2);
;     ...
;             PG8_LDA(At, 1, 1); PG8_STAGE(PG8_SB(1, 0), b3, voffB); PG8_STAGE(PG8_SB(1, 1), b3 + hstep, voffB); PG8_STAGE(PG8_SA(1, 0), a3, voffA);
;             PG8_WAIT_V(8); PG8_WAIT_L(0); PG8_BAR; PG8_MMA(1, 0, At, B0); PG8_MMA(1, 1, At, B1); PG8_BAR; PG8_SCHED;
	s_add_i32 s42, s64, s44
	v_lshl_add_u64 v[150:151], v[150:151], 0, s[18:19]
	s_mov_b32 m0, s42
	ds_read_b128 v[188:191], v166 offset:49152
	ds_read_b128 v[196:199], v166 offset:50176
	ds_read_b128 v[200:203], v166 offset:51200
	ds_read_b128 v[204:207], v166 offset:52224
	ds_read_b128 v[208:211], v166 offset:53248
	ds_read_b128 v[212:215], v166 offset:54272
	ds_read_b128 v[216:219], v166 offset:55296
	ds_read_b128 v[220:223], v166 offset:56320
	global_load_lds_dwordx4 v[150:151], off
	s_add_i32 m0, s42, 0x2000
	s_add_u32 s40, s40, 0x80080
	v_lshl_add_u64 v[150:151], v[192:193], 0, s[18:19]
	s_addc_u32 s41, s41, 0
	s_add_i32 s42, s65, s44
	global_load_lds_dwordx4 v[150:151], off
	v_lshl_add_u64 v[150:151], s[40:41], 0, v[130:131]
	s_mov_b32 m0, s42
	s_nop 0
	global_load_lds_dwordx4 v[150:151], off
	v_lshl_add_u64 v[150:151], s[40:41], 0, v[134:135]
	s_add_i32 m0, s42, 0x2000
	s_nop 0
	global_load_lds_dwordx4 v[150:151], off
	v_lshl_add_u64 v[150:151], v[224:225], 0, s[18:19]
	s_mov_b32 m0, s52
	s_nop 0
	global_load_lds_dwordx4 v[150:151], off
	v_lshl_add_u64 v[150:151], v[226:227], 0, s[18:19]
	s_mov_b32 m0, s53
	s_nop 0
	global_load_lds_dwordx4 v[150:151], off
	s_waitcnt vmcnt(8)
	s_waitcnt lgkmcnt(0)
	s_barrier
	s_setprio 1
	s_waitcnt lgkmcnt(0)
	v_mfma_f32_16x16x32_bf16 v[60:63], v[146:149], v[188:191], v[60:63]
	v_mfma_f32_16x16x32_bf16 v[56:59], v[158:161], v[188:191], v[56:59]
	v_mfma_f32_16x16x32_bf16 v[40:43], v[158:161], v[200:203], v[40:43]
	v_mfma_f32_16x16x32_bf16 v[44:47], v[146:149], v[200:203], v[44:47]
	v_mfma_f32_16x16x32_bf16 v[28:31], v[146:149], v[208:211], v[28:31]
	v_mfma_f32_16x16x32_bf16 v[24:27], v[158:161], v[208:211], v[24:27]
	v_mfma_f32_16x16x32_bf16 v[8:11], v[158:161], v[216:219], v[8:11]
	v_mfma_f32_16x16x32_bf16 v[12:15], v[146:149], v[216:219], v[12:15]
	v_mfma_f32_16x16x32_bf16 v[60:63], v[154:157], v[196:199], v[60:63]
	v_mfma_f32_16x16x32_bf16 v[56:59], v[168:171], v[196:199], v[56:59]
	v_mfma_f32_16x16x32_bf16 v[40:43], v[168:171], v[204:207], v[40:43]
	v_mfma_f32_16x16x32_bf16 v[44:47], v[154:157], v[204:207], v[44:47]
	v_mfma_f32_16x16x32_bf16 v[28:31], v[154:157], v[212:215], v[28:31]
	v_mfma_f32_16x16x32_bf16 v[24:27], v[168:171], v[212:215], v[24:27]
	v_mfma_f32_16x16x32_bf16 v[8:11], v[168:171], v[220:223], v[8:11]
	v_mfma_f32_16x16x32_bf16 v[12:15], v[154:157], v[220:223], v[12:15]
	s_setprio 0
	s_setprio 1
	v_mfma_f32_16x16x32_bf16 v[52:55], v[172:175], v[188:191], v[52:55]
	v_mfma_f32_16x16x32_bf16 v[48:51], v[180:183], v[188:191], v[48:51]
	v_mfma_f32_16x16x32_bf16 v[32:35], v[180:183], v[200:203], v[32:35]
	v_mfma_f32_16x16x32_bf16 v[36:39], v[172:175], v[200:203], v[36:39]
	v_mfma_f32_16x16x32_bf16 v[20:23], v[172:175], v[208:211], v[20:23]
	v_mfma_f32_16x16x32_bf16 v[16:19], v[180:183], v[208:211], v[16:19]
	v_mfma_f32_16x16x32_bf16 v[0:3], v[180:183], v[216:219], v[0:3]
	v_mfma_f32_16x16x32_bf16 v[4:7], v[172:175], v[216:219], v[4:7]
	v_mfma_f32_16x16x32_bf16 v[52:55], v[176:179], v[196:199], v[52:55]
	v_mfma_f32_16x16x32_bf16 v[48:51], v[184:187], v[196:199], v[48:51]
	v_mfma_f32_16x16x32_bf16 v[32:35], v[184:187], v[204:207], v[32:35]
	v_mfma_f32_16x16x32_bf16 v[36:39], v[176:179], v[204:207], v[36:39]
	v_mfma_f32_16x16x32_bf16 v[20:23], v[176:179], v[212:215], v[20:23]
	v_mfma_f32_16x16x32_bf16 v[16:19], v[184:187], v[212:215], v[16:19]
	v_mfma_f32_16x16x32_bf16 v[0:3], v[184:187], v[220:223], v[0:3]
	v_mfma_f32_16x16x32_bf16 v[4:7], v[176:179], v[220:223], v[4:7]
	s_setprio 0
	s_barrier
	s_add_i32 s63, s63, 2
	s_add_u32 s36, s36, 0x100
	s_addc_u32 s37, s37, 0
	s_add_u32 s61, s61, 0x100
	s_addc_u32 s62, s62, 0
	s_cmp_gt_u32 s63, 29
	s_cbranch_scc0 .LBB0_495
	s_and_b64 vcc, exec, s[16:17]
	s_cbranch_vccz .LBB0_498
	s_barrier

; #define PG8_STAGE(bufoff, gbase, voff) do { _Pragma("unroll") for (int _i = 0; _i < 2; ++_i) \
;         __builtin_amdgcn_global_load_lds((const unsigned*)((const char*)(gbase) + (voff)[_i]), (PG8_LAS unsigned*)(lds + (bufoff) + ldsw + _i * 8192), 16, 0, 0); } while (0)
; #define PG8_LDA(dst, b, h) do { _Pragma("unroll") for (int m = 0; m < 4; ++m) _Pragma("unroll") for (int k = 0; k < 2; ++k) dst[m][k] = *(const PG8_LAS bf16x8*)(lds + PG8_SA(b, h) + aoff + m * 2048 + k * 1024); } while (0)
; #define PG8_LDB(dst, b, h) do { _Pragma("unroll") for (int n = 0; n < 2; ++n) _Pragma("unroll") for (int k = 0; k < 2; ++k) dst[n][k] = *(const PG8_LAS bf16x8*)(lds + PG8_SB(b, h) + boff + n * 2048 + k * 1024); } while (0)
; #define PG8_MMA(ai, bj, At, Bt) do { __builtin_amdgcn_s_setprio(1); _Pragma("unroll") for (int m = 0; m < 4; ++m) _Pragma("unroll") for (int n = 0; n < 2; ++n) _Pragma("unroll") for (int k = 0; k < 2; ++k) \
;         acc[ai][bj][m][n] = __builtin_amdgcn_mfma_f32_16x16x32_bf16(Bt[n][k], At[m][k], acc[ai][bj][m][n], 0, 0, 0); __builtin_amdgcn_s_setprio(0); } while (0)
; #define PG8_WAIT_V(n) asm volatile("s_waitcnt vmcnt(" #n ")" ::: "memory")
; #define PG8_WAIT_L(n) asm volatile("s_waitcnt lgkmcnt(" #n ")" ::: "memory")
; #define PG8_BAR __builtin_amdgcn_s_barrier()
; #define PG8_SCHED __builtin_amdgcn_sched_barrier(0)
; template <class Epi, class Sched, bool ALIGN_EPI = false, bool SP2 = false>
; __device__ __forceinline__ void gemm_phase(PG8_LAS unsigned char* lds, const Gemm g, const Sched& S, const Epi& E, const int wave_) {
;     ...
;             const char* a1 = cA + (size_t)(t + 1) * kstep;
;             const char* a2 = last ? nA : cA + (size_t)(t + 2) * kstep; const char* b2 = last ? nB : cB + (size_t)(t + 2) * kstep;
;             const char* a3 = a2 + kstep; const char* b3 = b2 + kstep;
;     ...
;             PG8_LDB(B0, 0, 0); PG8_LDB(B1, 0, 1); PG8_SCHED; PG8_LDA(At, 0, 0); PG8_STAGE(PG8_SA(1, 1), a1 + hstep, voffA);
;             PG8_WAIT_V(8); PG8_WAIT_L(0); PG8_BAR; PG8_MMA(0, 0, At, B0); PG8_MMA(0, 1, At, B1); PG8_BAR; PG8_SCHED;
;             PG8_LDA(At, 0, 1); PG8_STAGE(PG8_SB(0, 0), b2, voffB); PG8_STAGE(PG8_SB(0, 1), b2 + hstep, voffB); PG8_STAGE(PG8_SA(0, 0), a2, voffA);
.LBB0_700:
	ds_read_b128 v[128:131], v187
	ds_read_b128 v[132:135], v187 offset:1024
	ds_read_b128 v[136:139], v187 offset:2048
	ds_read_b128 v[140:143], v187 offset:3072
	ds_read_b128 v[160:163], v188
	ds_read_b128 v[164:167], v188 offset:1024
	ds_read_b128 v[168:171], v188 offset:2048
	ds_read_b128 v[172:175], v188 offset:3072
	s_add_u32 s36, s34, 0xfff80080
	s_addc_u32 s37, s35, -1
	s_cmp_eq_u32 s58, 28
	s_cselect_b32 s41, s23, s37
	s_cselect_b32 s40, s29, s36
	s_cselect_b32 s37, s21, s57
	s_cselect_b32 s36, s31, s56
	v_lshl_add_u64 v[180:181], s[34:35], 0, v[152:153]
	s_add_i32 m0, s42, 0xc000
	ds_read_b128 v[176:179], v189
	ds_read_b128 v[196:199], v189 offset:1024
	ds_read_b128 v[200:203], v189 offset:2048
	ds_read_b128 v[204:207], v189 offset:3072
	ds_read_b128 v[208:211], v189 offset:4096
	ds_read_b128 v[212:215], v189 offset:5120
	ds_read_b128 v[216:219], v189 offset:6144
	ds_read_b128 v[220:223], v189 offset:7168
	global_load_lds_dwordx4 v[180:181], off
	v_lshl_add_u64 v[180:181], s[34:35], 0, v[154:155]
	s_add_i32 m0, s42, 0xe000
	s_nop 0
	global_load_lds_dwordx4 v[180:181], off
	s_waitcnt vmcnt(8)
	s_waitcnt lgkmcnt(0)
	s_barrier
	s_setprio 1
	s_waitcnt lgkmcnt(0)
	v_mfma_f32_16x16x32_bf16 v[40:43], v[128:131], v[176:179], v[40:43]
	v_mfma_f32_16x16x32_bf16 v[36:39], v[136:139], v[176:179], v[36:39]
	v_mfma_f32_16x16x32_bf16 v[64:67], v[136:139], v[200:203], v[64:67]
	v_mfma_f32_16x16x32_bf16 v[68:71], v[128:131], v[200:203], v[68:71]
	v_mfma_f32_16x16x32_bf16 v[100:103], v[128:131], v[208:211], v[100:103]
	v_mfma_f32_16x16x32_bf16 v[96:99], v[136:139], v[208:211], v[96:99]
	v_mfma_f32_16x16x32_bf16 v[120:123], v[136:139], v[216:219], v[120:123]
	v_mfma_f32_16x16x32_bf16 v[124:127], v[128:131], v[216:219], v[124:127]
	v_mfma_f32_16x16x32_bf16 v[40:43], v[132:135], v[196:199], v[40:43]
	v_mfma_f32_16x16x32_bf16 v[36:39], v[140:143], v[196:199], v[36:39]
	v_mfma_f32_16x16x32_bf16 v[64:67], v[140:143], v[204:207], v[64:67]
	v_mfma_f32_16x16x32_bf16 v[68:71], v[132:135], v[204:207], v[68:71]
	v_mfma_f32_16x16x32_bf16 v[100:103], v[132:135], v[212:215], v[100:103]
	v_mfma_f32_16x16x32_bf16 v[96:99], v[140:143], v[212:215], v[96:99]
	v_mfma_f32_16x16x32_bf16 v[120:123], v[140:143], v[220:223], v[120:123]
	v_mfma_f32_16x16x32_bf16 v[124:127], v[132:135], v[220:223], v[124:127]
	s_setprio 0
	s_setprio 1
	v_mfma_f32_16x16x32_bf16 v[44:47], v[160:163], v[176:179], v[44:47]
	v_mfma_f32_16x16x32_bf16 v[52:55], v[168:171], v[176:179], v[52:55]
	v_mfma_f32_16x16x32_bf16 v[76:79], v[168:171], v[200:203], v[76:79]
	v_mfma_f32_16x16x32_bf16 v[72:75], v[160:163], v[200:203], v[72:75]
	v_mfma_f32_16x16x32_bf16 v[104:107], v[160:163], v[208:211], v[104:107]
	v_mfma_f32_16x16x32_bf16 v[108:111], v[168:171], v[208:211], v[108:111]
	v_mfma_f32_16x16x32_bf16 v[112:115], v[168:171], v[216:219], v[112:115]
	v_mfma_f32_16x16x32_bf16 v[116:119], v[160:163], v[216:219], v[116:119]
	v_mfma_f32_16x16x32_bf16 v[44:47], v[164:167], v[196:199], v[44:47]
	v_mfma_f32_16x16x32_bf16 v[52:55], v[172:175], v[196:199], v[52:55]
	v_mfma_f32_16x16x32_bf16 v[76:79], v[172:175], v[204:207], v[76:79]
	v_mfma_f32_16x16x32_bf16 v[72:75], v[164:167], v[204:207], v[72:75]
	v_mfma_f32_16x16x32_bf16 v[104:107], v[164:167], v[212:215], v[104:107]
	v_mfma_f32_16x16x32_bf16 v[108:111], v[172:175], v[212:215], v[108:111]
	v_mfma_f32_16x16x32_bf16 v[112:115], v[172:175], v[220:223], v[112:115]
	v_mfma_f32_16x16x32_bf16 v[116:119], v[164:167], v[220:223], v[116:119]
	s_setprio 0
	s_barrier
	s_add_i32 s59, s54, s2
	v_lshl_add_u64 v[180:181], s[36:37], 0, v[146:147]
	s_mov_b32 m0, s59
	ds_read_b128 v[176:179], v189 offset:16384
	ds_read_b128 v[196:199], v189 offset:17408
	ds_read_b128 v[200:203], v189 offset:18432
	ds_read_b128 v[204:207], v189 offset:19456
	ds_read_b128 v[208:211], v189 offset:20480
	ds_read_b128 v[212:215], v189 offset:21504
	ds_read_b128 v[216:219], v189 offset:22528
	ds_read_b128 v[220:223], v189 offset:23552
	global_load_lds_dwordx4 v[180:181], off
	s_add_i32 m0, s59, 0x2000
	s_add_u32 s60, s36, 0x80000
	v_lshl_add_u64 v[192:193], s[36:37], 0, v[150:151]
	s_addc_u32 s61, s37, 0
	s_add_i32 s59, s55, s2
	global_load_lds_dwordx4 v[192:193], off
	v_lshl_add_u64 v[224:225], s[60:61], 0, v[146:147]
	s_mov_b32 m0, s59
	v_lshl_add_u64 v[226:227], s[40:41], 0, v[148:149]
	global_load_lds_dwordx4 v[224:225], off
	v_lshl_add_u64 v[224:225], s[60:61], 0, v[150:151]
	s_add_i32 m0, s59, 0x2000
	s_nop 0
	global_load_lds_dwordx4 v[224:225], off
	v_lshl_add_u64 v[224:225], s[40:41], 0, v[144:145]
	s_mov_b32 m0, s42
	s_nop 0
	global_load_lds_dwordx4 v[224:225], off
	s_mov_b32 m0, s43
	s_nop 0
	global_load_lds_dwordx4 v[226:227], off
	s_waitcnt vmcnt(8)
	s_waitcnt lgkmcnt(0)
	s_barrier
; #define PG8_STAGE(bufoff, gbase, voff) do { _Pragma("unroll") for (int _i = 0; _i < 2; ++_i) \
;         __builtin_amdgcn_global_load_lds((const unsigned*)((const char*)(gbase) + (voff)[_i]), (PG8_LAS unsigned*)(lds + (bufoff) + ldsw + _i * 8192), 16, 0, 0); } while (0)
; #define PG8_LDA(dst, b, h) do { _Pragma("unroll") for (int m = 0; m < 4; ++m) _Pragma("unroll") for (int k = 0; k < 2; ++k) dst[m][k] = *(const PG8_LAS bf16x8*)(lds + PG8_SA(b, h) + aoff + m * 2048 + k * 1024); } while (0)
; #define PG8_LDB(dst, b, h) do { _Pragma("unroll") for (int n = 0; n < 2; ++n) _Pragma("unroll") for (int k = 0; k < 2; ++k) dst[n][k] = *(const PG8_LAS bf16x8*)(lds + PG8_SB(b, h) + boff + n * 2048 + k * 1024); } while (0)
; #define PG8_MMA(ai, bj, At, Bt) do { __builtin_amdgcn_s_setprio(1); _Pragma("unroll") for (int m = 0; m < 4; ++m) _Pragma("unroll") for (int n = 0; n < 2; ++n) _Pragma("unroll") for (int k = 0; k < 2; ++k) \
;         acc[ai][bj][m][n] = __builtin_amdgcn_mfma_f32_16x16x32_bf16(Bt[n][k], At[m][k], acc[ai][bj][m][n], 0, 0, 0); __builtin_amdgcn_s_setprio(0); } while (0)
; #define PG8_WAIT_V(n) asm volatile("s_waitcnt vmcnt(" #n ")" ::: "memory")
; #define PG8_WAIT_L(n) asm volatile("s_waitcnt lgkmcnt(" #n ")" ::: "memory")
; #define PG8_BAR __builtin_amdgcn_s_barrier()
; #define PG8_SCHED __builtin_amdgcn_sched_barrier(0)
; template <class Epi, class Sched, bool ALIGN_EPI = false, bool SP2 = false>
; __device__ __forceinline__ void gemm_phase(PG8_LAS unsigned char* lds, const Gemm g, const Sched& S, const Epi& E, const int wave_) {
;     ...
;             PG8_WAIT_V(8); PG8_WAIT_L(0); PG8_BAR; PG8_MMA(1, 0, At, B0); PG8_MMA(1, 1, At, B1); PG8_BAR; PG8_SCHED;
;             PG8_LDB(B0, 1, 0); PG8_LDB(B1, 1, 1); PG8_SCHED; PG8_LDA(At, 1, 0); PG8_STAGE(PG8_SA(0, 1), a2 + hstep, voffA);
;             PG8_WAIT_V(8); PG8_WAIT_L(0); PG8_BAR; PG8_MMA(0, 0, At, B0); PG8_MMA(0, 1, At, B1); PG8_BAR; PG8_SCHED;
	s_setprio 1
	s_waitcnt lgkmcnt(0)
	v_mfma_f32_16x16x32_bf16 v[92:95], v[128:131], v[176:179], v[92:95]
	v_mfma_f32_16x16x32_bf16 v[88:91], v[136:139], v[176:179], v[88:91]
	v_mfma_f32_16x16x32_bf16 v[56:59], v[136:139], v[200:203], v[56:59]
	v_mfma_f32_16x16x32_bf16 v[60:63], v[128:131], v[200:203], v[60:63]
	v_mfma_f32_16x16x32_bf16 v[28:31], v[128:131], v[208:211], v[28:31]
	v_mfma_f32_16x16x32_bf16 v[24:27], v[136:139], v[208:211], v[24:27]
	v_mfma_f32_16x16x32_bf16 v[8:11], v[136:139], v[216:219], v[8:11]
	v_mfma_f32_16x16x32_bf16 v[12:15], v[128:131], v[216:219], v[12:15]
	v_mfma_f32_16x16x32_bf16 v[92:95], v[132:135], v[196:199], v[92:95]
	v_mfma_f32_16x16x32_bf16 v[88:91], v[140:143], v[196:199], v[88:91]
	v_mfma_f32_16x16x32_bf16 v[56:59], v[140:143], v[204:207], v[56:59]
	v_mfma_f32_16x16x32_bf16 v[60:63], v[132:135], v[204:207], v[60:63]
	v_mfma_f32_16x16x32_bf16 v[28:31], v[132:135], v[212:215], v[28:31]
	v_mfma_f32_16x16x32_bf16 v[24:27], v[140:143], v[212:215], v[24:27]
	v_mfma_f32_16x16x32_bf16 v[8:11], v[140:143], v[220:223], v[8:11]
	v_mfma_f32_16x16x32_bf16 v[12:15], v[132:135], v[220:223], v[12:15]
	s_setprio 0
	s_setprio 1
	v_mfma_f32_16x16x32_bf16 v[84:87], v[160:163], v[176:179], v[84:87]
	v_mfma_f32_16x16x32_bf16 v[80:83], v[168:171], v[176:179], v[80:83]
	v_mfma_f32_16x16x32_bf16 v[32:35], v[168:171], v[200:203], v[32:35]
	v_mfma_f32_16x16x32_bf16 v[48:51], v[160:163], v[200:203], v[48:51]
	v_mfma_f32_16x16x32_bf16 v[20:23], v[160:163], v[208:211], v[20:23]
	v_mfma_f32_16x16x32_bf16 v[16:19], v[168:171], v[208:211], v[16:19]
	v_mfma_f32_16x16x32_bf16 v[0:3], v[168:171], v[216:219], v[0:3]
	v_mfma_f32_16x16x32_bf16 v[4:7], v[160:163], v[216:219], v[4:7]
	v_mfma_f32_16x16x32_bf16 v[84:87], v[164:167], v[196:199], v[84:87]
	v_mfma_f32_16x16x32_bf16 v[80:83], v[172:175], v[196:199], v[80:83]
	v_mfma_f32_16x16x32_bf16 v[32:35], v[172:175], v[204:207], v[32:35]
	v_mfma_f32_16x16x32_bf16 v[48:51], v[164:167], v[204:207], v[48:51]
	v_mfma_f32_16x16x32_bf16 v[20:23], v[164:167], v[212:215], v[20:23]
	v_mfma_f32_16x16x32_bf16 v[16:19], v[172:175], v[212:215], v[16:19]
	v_mfma_f32_16x16x32_bf16 v[0:3], v[172:175], v[220:223], v[0:3]
	v_mfma_f32_16x16x32_bf16 v[4:7], v[164:167], v[220:223], v[4:7]
	s_setprio 0
	s_barrier
	s_add_i32 s59, 0, 0x18000
	s_add_i32 s60, 0, 0x1c000
	v_add_u32_e32 v140, s59, v183
	v_add_u32_e32 v172, s60, v183
	ds_read_b128 v[128:131], v140
	ds_read_b128 v[132:135], v140 offset:1024
	ds_read_b128 v[136:139], v140 offset:2048
	ds_read_b128 v[140:143], v140 offset:3072
	ds_read_b128 v[160:163], v172
	ds_read_b128 v[164:167], v172 offset:1024
	ds_read_b128 v[168:171], v172 offset:2048
	ds_read_b128 v[172:175], v172 offset:3072
	s_add_u32 s40, s40, 0x80000
	s_addc_u32 s41, s41, 0
	s_mov_b32 m0, s44
	v_lshl_add_u64 v[228:229], s[40:41], 0, v[144:145]
	ds_read_b128 v[176:179], v189 offset:32768
	ds_read_b128 v[196:199], v189 offset:33792
	ds_read_b128 v[200:203], v189 offset:34816
	ds_read_b128 v[204:207], v189 offset:35840
	ds_read_b128 v[208:211], v189 offset:36864
	ds_read_b128 v[212:215], v189 offset:37888
	ds_read_b128 v[216:219], v189 offset:38912
	ds_read_b128 v[220:223], v189 offset:39936
	global_load_lds_dwordx4 v[228:229], off
	v_lshl_add_u64 v[228:229], s[40:41], 0, v[148:149]
	s_mov_b32 m0, s45
	s_nop 0
	global_load_lds_dwordx4 v[228:229], off
	s_waitcnt vmcnt(8)
	s_waitcnt lgkmcnt(0)
	s_barrier
	s_setprio 1
	s_waitcnt lgkmcnt(0)
	v_mfma_f32_16x16x32_bf16 v[40:43], v[128:131], v[176:179], v[40:43]
	v_mfma_f32_16x16x32_bf16 v[36:39], v[136:139], v[176:179], v[36:39]
	v_mfma_f32_16x16x32_bf16 v[64:67], v[136:139], v[200:203], v[64:67]
	v_mfma_f32_16x16x32_bf16 v[68:71], v[128:131], v[200:203], v[68:71]
	v_mfma_f32_16x16x32_bf16 v[100:103], v[128:131], v[208:211], v[100:103]
	v_mfma_f32_16x16x32_bf16 v[96:99], v[136:139], v[208:211], v[96:99]
	v_mfma_f32_16x16x32_bf16 v[120:123], v[136:139], v[216:219], v[120:123]
	v_mfma_f32_16x16x32_bf16 v[124:127], v[128:131], v[216:219], v[124:127]
	v_mfma_f32_16x16x32_bf16 v[40:43], v[132:135], v[196:199], v[40:43]
	v_mfma_f32_16x16x32_bf16 v[36:39], v[140:143], v[196:199], v[36:39]
	v_mfma_f32_16x16x32_bf16 v[64:67], v[140:143], v[204:207], v[64:67]
	v_mfma_f32_16x16x32_bf16 v[68:71], v[132:135], v[204:207], v[68:71]
	v_mfma_f32_16x16x32_bf16 v[100:103], v[132:135], v[212:215], v[100:103]
	v_mfma_f32_16x16x32_bf16 v[96:99], v[140:143], v[212:215], v[96:99]
	v_mfma_f32_16x16x32_bf16 v[120:123], v[140:143], v[220:223], v[120:123]
	v_mfma_f32_16x16x32_bf16 v[124:127], v[132:135], v[220:223], v[124:127]
	s_setprio 0
	s_setprio 1
	v_mfma_f32_16x16x32_bf16 v[44:47], v[160:163], v[176:179], v[44:47]
	v_mfma_f32_16x16x32_bf16 v[52:55], v[168:171], v[176:179], v[52:55]
	v_mfma_f32_16x16x32_bf16 v[76:79], v[168:171], v[200:203], v[76:79]
	v_mfma_f32_16x16x32_bf16 v[72:75], v[160:163], v[200:203], v[72:75]
	v_mfma_f32_16x16x32_bf16 v[104:107], v[160:163], v[208:211], v[104:107]
	v_mfma_f32_16x16x32_bf16 v[108:111], v[168:171], v[208:211], v[108:111]
	v_mfma_f32_16x16x32_bf16 v[112:115], v[168:171], v[216:219], v[112:115]
	v_mfma_f32_16x16x32_bf16 v[116:119], v[160:163], v[216:219], v[116:119]
	v_mfma_f32_16x16x32_bf16 v[44:47], v[164:167], v[196:199], v[44:47]
	v_mfma_f32_16x16x32_bf16 v[52:55], v[172:175], v[196:199], v[52:55]
	v_mfma_f32_16x16x32_bf16 v[76:79], v[172:175], v[204:207], v[76:79]
	v_mfma_f32_16x16x32_bf16 v[72:75], v[164:167], v[204:207], v[72:75]
	v_mfma_f32_16x16x32_bf16 v[104:107], v[164:167], v[212:215], v[104:107]
	v_mfma_f32_16x16x32_bf16 v[108:111], v[172:175], v[212:215], v[108:111]
	v_mfma_f32_16x16x32_bf16 v[112:115], v[172:175], v[220:223], v[112:115]
	v_mfma_f32_16x16x32_bf16 v[116:119], v[164:167], v[220:223], v[116:119]
	s_setprio 0
	s_barrier
; #define PG8_STAGE(bufoff, gbase, voff) do { _Pragma("unroll") for (int _i = 0; _i < 2; ++_i) \
;         __builtin_amdgcn_global_load_lds((const unsigned*)((const char*)(gbase) + (voff)[_i]), (PG8_LAS unsigned*)(lds + (bufoff) + ldsw + _i * 8192), 16, 0, 0); } while (0)
; #define PG8_LDA(dst, b, h) do { _Pragma("unroll") for (int m = 0; m < 4; ++m) _Pragma("unroll") for (int k = 0; k < 2; ++k) dst[m][k] = *(const PG8_LAS bf16x8*)(lds + PG8_SA(b, h) + aoff + m * 2048 + k * 1024); } while (0)
; #define PG8_MMA(ai, bj, At, Bt) do { __builtin_amdgcn_s_setprio(1); _Pragma("unroll") for (int m = 0; m < 4; ++m) _Pragma("unroll") for (int n = 0; n < 2; ++n) _Pragma("unroll") for (int k = 0; k < 2; ++k) \
;         acc[ai][bj][m][n] = __builtin_amdgcn_mfma_f32_16x16x32_bf16(Bt[n][k], At[m][k], acc[ai][bj][m][n], 0, 0, 0); __builtin_amdgcn_s_setprio(0); } while (0)
; #define PG8_WAIT_V(n) asm volatile("s_waitcnt vmcnt(" #n ")" ::: "memory")
; #define PG8_WAIT_L(n) asm volatile("s_waitcnt lgkmcnt(" #n ")" ::: "memory")
; #define PG8_BAR __builtin_amdgcn_s_barrier()
; #define PG8_SCHED __builtin_amdgcn_sched_barrier(0)
; template <class Epi, class Sched, bool ALIGN_EPI = false, bool SP2 = false>
; __device__ __forceinline__ void gemm_phase(PG8_LAS unsigned char* lds, const Gemm g, const Sched& S, const Epi& E, const int wave_) {
;     ...
;         for (int t = 0; t < nt; t += 2) {
;             const bool last = (t == nt - 2);
;     ...
;             PG8_LDA(At, 1, 1); PG8_STAGE(PG8_SB(1, 0), b3, voffB); PG8_STAGE(PG8_SB(1, 1), b3 + hstep, voffB); PG8_STAGE(PG8_SA(1, 0), a3, voffA);
;             PG8_WAIT_V(8); PG8_WAIT_L(0); PG8_BAR; PG8_MMA(1, 0, At, B0); PG8_MMA(1, 1, At, B1); PG8_BAR; PG8_SCHED;
	s_add_i32 s40, s59, s2
	v_lshl_add_u64 v[180:181], v[180:181], 0, s[18:19]
	s_mov_b32 m0, s40
	ds_read_b128 v[176:179], v189 offset:49152
	ds_read_b128 v[196:199], v189 offset:50176
	ds_read_b128 v[200:203], v189 offset:51200
	ds_read_b128 v[204:207], v189 offset:52224
	ds_read_b128 v[208:211], v189 offset:53248
	ds_read_b128 v[212:215], v189 offset:54272
	ds_read_b128 v[216:219], v189 offset:55296
	ds_read_b128 v[220:223], v189 offset:56320
	global_load_lds_dwordx4 v[180:181], off
	s_add_i32 m0, s40, 0x2000
	s_add_u32 s36, s36, 0x80080
	v_lshl_add_u64 v[180:181], v[192:193], 0, s[18:19]
	s_addc_u32 s37, s37, 0
	s_add_i32 s40, s60, s2
	global_load_lds_dwordx4 v[180:181], off
	v_lshl_add_u64 v[180:181], s[36:37], 0, v[146:147]
	s_mov_b32 m0, s40
	s_nop 0
	global_load_lds_dwordx4 v[180:181], off
	v_lshl_add_u64 v[180:181], s[36:37], 0, v[150:151]
	s_add_i32 m0, s40, 0x2000
	s_nop 0
	global_load_lds_dwordx4 v[180:181], off
	v_lshl_add_u64 v[180:181], v[224:225], 0, s[18:19]
	s_mov_b32 m0, s51
	s_nop 0
	global_load_lds_dwordx4 v[180:181], off
	v_lshl_add_u64 v[180:181], v[226:227], 0, s[18:19]
	s_mov_b32 m0, s52
	s_nop 0
	global_load_lds_dwordx4 v[180:181], off
	s_waitcnt vmcnt(8)
	s_waitcnt lgkmcnt(0)
	s_barrier
	s_setprio 1
	s_waitcnt lgkmcnt(0)
	v_mfma_f32_16x16x32_bf16 v[92:95], v[128:131], v[176:179], v[92:95]
	v_mfma_f32_16x16x32_bf16 v[88:91], v[136:139], v[176:179], v[88:91]
	v_mfma_f32_16x16x32_bf16 v[56:59], v[136:139], v[200:203], v[56:59]
	v_mfma_f32_16x16x32_bf16 v[60:63], v[128:131], v[200:203], v[60:63]
	v_mfma_f32_16x16x32_bf16 v[28:31], v[128:131], v[208:211], v[28:31]
	v_mfma_f32_16x16x32_bf16 v[24:27], v[136:139], v[208:211], v[24:27]
	v_mfma_f32_16x16x32_bf16 v[8:11], v[136:139], v[216:219], v[8:11]
	v_mfma_f32_16x16x32_bf16 v[12:15], v[128:131], v[216:219], v[12:15]
	v_mfma_f32_16x16x32_bf16 v[92:95], v[132:135], v[196:199], v[92:95]
	v_mfma_f32_16x16x32_bf16 v[88:91], v[140:143], v[196:199], v[88:91]
	v_mfma_f32_16x16x32_bf16 v[56:59], v[140:143], v[204:207], v[56:59]
	v_mfma_f32_16x16x32_bf16 v[60:63], v[132:135], v[204:207], v[60:63]
	v_mfma_f32_16x16x32_bf16 v[28:31], v[132:135], v[212:215], v[28:31]
	v_mfma_f32_16x16x32_bf16 v[24:27], v[140:143], v[212:215], v[24:27]
	v_mfma_f32_16x16x32_bf16 v[8:11], v[140:143], v[220:223], v[8:11]
	v_mfma_f32_16x16x32_bf16 v[12:15], v[132:135], v[220:223], v[12:15]
	s_setprio 0
	s_setprio 1
	v_mfma_f32_16x16x32_bf16 v[84:87], v[160:163], v[176:179], v[84:87]
	v_mfma_f32_16x16x32_bf16 v[80:83], v[168:171], v[176:179], v[80:83]
	v_mfma_f32_16x16x32_bf16 v[32:35], v[168:171], v[200:203], v[32:35]
	v_mfma_f32_16x16x32_bf16 v[48:51], v[160:163], v[200:203], v[48:51]
	v_mfma_f32_16x16x32_bf16 v[20:23], v[160:163], v[208:211], v[20:23]
	v_mfma_f32_16x16x32_bf16 v[16:19], v[168:171], v[208:211], v[16:19]
	v_mfma_f32_16x16x32_bf16 v[0:3], v[168:171], v[216:219], v[0:3]
	v_mfma_f32_16x16x32_bf16 v[4:7], v[160:163], v[216:219], v[4:7]
	v_mfma_f32_16x16x32_bf16 v[84:87], v[164:167], v[196:199], v[84:87]
	v_mfma_f32_16x16x32_bf16 v[80:83], v[172:175], v[196:199], v[80:83]
	v_mfma_f32_16x16x32_bf16 v[32:35], v[172:175], v[204:207], v[32:35]
	v_mfma_f32_16x16x32_bf16 v[48:51], v[164:167], v[204:207], v[48:51]
	v_mfma_f32_16x16x32_bf16 v[20:23], v[164:167], v[212:215], v[20:23]
	v_mfma_f32_16x16x32_bf16 v[16:19], v[172:175], v[212:215], v[16:19]
	v_mfma_f32_16x16x32_bf16 v[0:3], v[172:175], v[220:223], v[0:3]
	v_mfma_f32_16x16x32_bf16 v[4:7], v[164:167], v[220:223], v[4:7]
	s_setprio 0
	s_barrier
	s_add_i32 s58, s58, 2
	s_add_u32 s34, s34, 0x100
	s_addc_u32 s35, s35, 0
	s_add_u32 s56, s56, 0x100
	s_addc_u32 s57, s57, 0
	s_cmp_gt_u32 s58, 29
	s_cbranch_scc0 .LBB0_700
	s_and_b64 vcc, exec, s[14:15]
	s_cbranch_vccz .LBB0_703
	s_barrier
